# scan waves: next-step LDS reads issued after every VALU instruction instead of every second (gen_scan5.py) on top of v190
# baseline (speedup 1.0000x reference)
.LBB0_390:
	s_and_b32 s3, s2, 1
	s_mul_i32 s8, s3, 0x5000
	v_add_u32_e32 v2, s8, v136
	s_mul_i32 s8, s2, 0xab
	s_bfe_u32 s8, s8, 0x70009
	s_mul_i32 s8, s8, 3
	s_sub_i32 s8, s2, s8
	s_and_b32 s8, s8, 0xff
	s_mulk_i32 s8, 0x1100
	v_add_u32_e32 v3, s8, v137
	v_lshl_add_u32 v1, s3, 12, v137
	ds_read_b128 v[176:179], v2 offset:4096
	ds_read_b128 v[180:183], v2 offset:4112
	ds_read_b128 v[200:203], v2 offset:12288
	ds_read_b128 v[204:207], v2 offset:12304
	ds_read_b64 v[216:217], v3 offset:40960
	ds_read_b128 v[184:187], v2 offset:0
	ds_read_b128 v[188:191], v2 offset:16
	ds_read_b128 v[192:195], v2 offset:8192
	ds_read_b128 v[196:199], v2 offset:8208
	s_waitcnt lgkmcnt(8)
	v_pk_mul_f32 v[164:165], v[72:73], v[176:177]
	ds_read_b128 v[208:211], v2 offset:16384
	v_pk_mul_f32 v[166:167], v[80:81], v[176:177]
	ds_read_b128 v[212:215], v2 offset:16400
	v_pk_fma_f32 v[164:165], v[74:75], v[178:179], v[164:165]
	ds_read_b128 v[4:7], v2 offset:4352
	v_pk_fma_f32 v[166:167], v[82:83], v[178:179], v[166:167]
	ds_read_b128 v[8:11], v2 offset:4368
	s_waitcnt lgkmcnt(11)
	v_pk_fma_f32 v[164:165], v[76:77], v[180:181], v[164:165]
	ds_read_b128 v[40:43], v2 offset:12544
	v_pk_fma_f32 v[166:167], v[84:85], v[180:181], v[166:167]
	ds_read_b128 v[44:47], v2 offset:12560
	v_pk_fma_f32 v[164:165], v[78:79], v[182:183], v[164:165]
	ds_read_b64 v[26:27], v3 offset:41216
	v_pk_fma_f32 v[166:167], v[86:87], v[182:183], v[166:167]
	ds_read_b128 v[12:15], v2 offset:256
	s_waitcnt lgkmcnt(12)
	v_pk_mul_f32 v[218:219], v[216:217], v[200:201] op_sel_hi:[0,1]
	ds_read_b128 v[28:31], v2 offset:272
	v_pk_mul_f32 v[226:227], v[216:217], v[200:201] op_sel:[1,0]
	ds_read_b128 v[32:35], v2 offset:8448
	v_pk_mul_f32 v[220:221], v[216:217], v[202:203] op_sel_hi:[0,1]
	ds_read_b128 v[36:39], v2 offset:8464
	v_pk_mul_f32 v[228:229], v[216:217], v[202:203] op_sel:[1,0]
	v_pk_mul_f32 v[222:223], v[216:217], v[204:205] op_sel_hi:[0,1]
	v_pk_mul_f32 v[230:231], v[216:217], v[204:205] op_sel:[1,0]
	v_pk_mul_f32 v[224:225], v[216:217], v[206:207] op_sel_hi:[0,1]
	v_pk_mul_f32 v[234:235], v[216:217], v[206:207] op_sel:[1,0]
	v_add_f32_e32 v172, v164, v165
	v_add_f32_e32 v174, v166, v167
	s_waitcnt lgkmcnt(14)
	v_pk_fma_f32 v[218:219], v[72:73], v[184:185], v[218:219]
	v_pk_fma_f32 v[226:227], v[80:81], v[184:185], v[226:227]
	v_pk_fma_f32 v[220:221], v[74:75], v[186:187], v[220:221]
	v_pk_fma_f32 v[228:229], v[82:83], v[186:187], v[228:229]
	v_add_f32_dpp v172, v172, v172 quad_perm:[1,0,3,2] row_mask:0xf bank_mask:0xf bound_ctrl:1
	v_add_f32_dpp v174, v174, v174 quad_perm:[1,0,3,2] row_mask:0xf bank_mask:0xf bound_ctrl:1
	s_waitcnt lgkmcnt(13)
	v_pk_fma_f32 v[222:223], v[76:77], v[188:189], v[222:223]
	v_pk_fma_f32 v[230:231], v[84:85], v[188:189], v[230:231]
	v_pk_fma_f32 v[224:225], v[78:79], v[190:191], v[224:225]
	v_pk_fma_f32 v[234:235], v[86:87], v[190:191], v[234:235]
	v_add_f32_dpp v172, v172, v172 quad_perm:[2,3,0,1] row_mask:0xf bank_mask:0xf bound_ctrl:1
	v_add_f32_dpp v174, v174, v174 quad_perm:[2,3,0,1] row_mask:0xf bank_mask:0xf bound_ctrl:1
	s_nop 0
	v_add_f32_dpp v172, v172, v172 row_half_mirror row_mask:0xf bank_mask:0xf bound_ctrl:1
	v_add_f32_dpp v174, v174, v174 row_half_mirror row_mask:0xf bank_mask:0xf bound_ctrl:1
	s_waitcnt lgkmcnt(12)
	v_pk_fma_f32 v[72:73], v[192:193], v[172:173], v[218:219] op_sel_hi:[1,0,1]
	v_pk_fma_f32 v[80:81], v[192:193], v[174:175], v[226:227] op_sel_hi:[1,0,1]
	v_pk_fma_f32 v[74:75], v[194:195], v[172:173], v[220:221] op_sel_hi:[1,0,1]
	v_pk_fma_f32 v[82:83], v[194:195], v[174:175], v[228:229] op_sel_hi:[1,0,1]
	s_waitcnt lgkmcnt(11)
	v_pk_fma_f32 v[76:77], v[196:197], v[172:173], v[222:223] op_sel_hi:[1,0,1]
	v_pk_fma_f32 v[84:85], v[196:197], v[174:175], v[230:231] op_sel_hi:[1,0,1]
	v_pk_fma_f32 v[78:79], v[198:199], v[172:173], v[224:225] op_sel_hi:[1,0,1]
	v_pk_fma_f32 v[86:87], v[198:199], v[174:175], v[234:235] op_sel_hi:[1,0,1]
	s_waitcnt lgkmcnt(8)
	v_pk_mul_f32 v[164:165], v[72:73], v[4:5]
	ds_read_b128 v[48:51], v2 offset:16640
	v_pk_mul_f32 v[166:167], v[80:81], v[4:5]
	ds_read_b128 v[52:55], v2 offset:16656
	v_pk_mul_f32 v[168:169], v[72:73], v[208:209]
	ds_read_b128 v[176:179], v2 offset:4608
	v_pk_mul_f32 v[170:171], v[80:81], v[208:209]
	ds_read_b128 v[180:183], v2 offset:4624
	v_pk_fma_f32 v[164:165], v[74:75], v[6:7], v[164:165]
	ds_read_b128 v[200:203], v2 offset:12800
	v_pk_fma_f32 v[166:167], v[82:83], v[6:7], v[166:167]
	ds_read_b128 v[204:207], v2 offset:12816
	v_pk_fma_f32 v[168:169], v[74:75], v[210:211], v[168:169]
	ds_read_b64 v[216:217], v3 offset:41472
	v_pk_fma_f32 v[170:171], v[82:83], v[210:211], v[170:171]
	ds_read_b128 v[184:187], v2 offset:512
	s_waitcnt lgkmcnt(15)
	v_pk_fma_f32 v[164:165], v[76:77], v[8:9], v[164:165]
	ds_read_b128 v[188:191], v2 offset:528
	v_pk_fma_f32 v[166:167], v[84:85], v[8:9], v[166:167]
	ds_read_b128 v[192:195], v2 offset:8704
	v_pk_fma_f32 v[168:169], v[76:77], v[212:213], v[168:169]
	ds_read_b128 v[196:199], v2 offset:8720
	v_pk_fma_f32 v[170:171], v[84:85], v[212:213], v[170:171]
	v_pk_fma_f32 v[164:165], v[78:79], v[10:11], v[164:165]
	v_pk_fma_f32 v[166:167], v[86:87], v[10:11], v[166:167]
	v_pk_fma_f32 v[168:169], v[78:79], v[214:215], v[168:169]
	v_pk_fma_f32 v[170:171], v[86:87], v[214:215], v[170:171]
	s_waitcnt lgkmcnt(15)
	v_pk_mul_f32 v[218:219], v[26:27], v[40:41] op_sel_hi:[0,1]
	v_pk_mul_f32 v[226:227], v[26:27], v[40:41] op_sel:[1,0]
	v_pk_mul_f32 v[220:221], v[26:27], v[42:43] op_sel_hi:[0,1]
	v_pk_mul_f32 v[228:229], v[26:27], v[42:43] op_sel:[1,0]
	v_pk_mul_f32 v[222:223], v[26:27], v[44:45] op_sel_hi:[0,1]
	v_pk_mul_f32 v[230:231], v[26:27], v[44:45] op_sel:[1,0]
	v_pk_mul_f32 v[224:225], v[26:27], v[46:47] op_sel_hi:[0,1]
	v_pk_mul_f32 v[234:235], v[26:27], v[46:47] op_sel:[1,0]
	v_add_f32_e32 v172, v164, v165
	v_add_f32_e32 v174, v166, v167
	v_add_f32_e32 v160, v168, v169
	v_add_f32_e32 v161, v170, v171
	s_waitcnt lgkmcnt(14)
	v_pk_fma_f32 v[218:219], v[72:73], v[12:13], v[218:219]
	v_pk_fma_f32 v[226:227], v[80:81], v[12:13], v[226:227]
	v_pk_fma_f32 v[220:221], v[74:75], v[14:15], v[220:221]
	v_pk_fma_f32 v[228:229], v[82:83], v[14:15], v[228:229]
	v_add_f32_dpp v172, v172, v172 quad_perm:[1,0,3,2] row_mask:0xf bank_mask:0xf bound_ctrl:1
	v_add_f32_dpp v174, v174, v174 quad_perm:[1,0,3,2] row_mask:0xf bank_mask:0xf bound_ctrl:1
	v_add_f32_dpp v160, v160, v160 quad_perm:[1,0,3,2] row_mask:0xf bank_mask:0xf bound_ctrl:1
	v_add_f32_dpp v161, v161, v161 quad_perm:[1,0,3,2] row_mask:0xf bank_mask:0xf bound_ctrl:1
	s_waitcnt lgkmcnt(13)
	v_pk_fma_f32 v[222:223], v[76:77], v[28:29], v[222:223]
	v_pk_fma_f32 v[230:231], v[84:85], v[28:29], v[230:231]
	v_pk_fma_f32 v[224:225], v[78:79], v[30:31], v[224:225]
	v_pk_fma_f32 v[234:235], v[86:87], v[30:31], v[234:235]
	v_add_f32_dpp v172, v172, v172 quad_perm:[2,3,0,1] row_mask:0xf bank_mask:0xf bound_ctrl:1
	v_add_f32_dpp v174, v174, v174 quad_perm:[2,3,0,1] row_mask:0xf bank_mask:0xf bound_ctrl:1
	v_add_f32_dpp v160, v160, v160 quad_perm:[2,3,0,1] row_mask:0xf bank_mask:0xf bound_ctrl:1
	v_add_f32_dpp v161, v161, v161 quad_perm:[2,3,0,1] row_mask:0xf bank_mask:0xf bound_ctrl:1
	v_add_f32_dpp v172, v172, v172 row_half_mirror row_mask:0xf bank_mask:0xf bound_ctrl:1
	v_add_f32_dpp v174, v174, v174 row_half_mirror row_mask:0xf bank_mask:0xf bound_ctrl:1
	v_add_f32_dpp v160, v160, v160 row_half_mirror row_mask:0xf bank_mask:0xf bound_ctrl:1
	v_add_f32_dpp v161, v161, v161 row_half_mirror row_mask:0xf bank_mask:0xf bound_ctrl:1
	s_waitcnt lgkmcnt(12)
	v_pk_fma_f32 v[72:73], v[32:33], v[172:173], v[218:219] op_sel_hi:[1,0,1]
	v_pk_fma_f32 v[80:81], v[32:33], v[174:175], v[226:227] op_sel_hi:[1,0,1]
	v_pk_fma_f32 v[74:75], v[34:35], v[172:173], v[220:221] op_sel_hi:[1,0,1]
	v_pk_fma_f32 v[82:83], v[34:35], v[174:175], v[228:229] op_sel_hi:[1,0,1]
	s_waitcnt lgkmcnt(11)
	v_pk_fma_f32 v[76:77], v[36:37], v[172:173], v[222:223] op_sel_hi:[1,0,1]
	v_pk_fma_f32 v[84:85], v[36:37], v[174:175], v[230:231] op_sel_hi:[1,0,1]
	v_pk_fma_f32 v[78:79], v[38:39], v[172:173], v[224:225] op_sel_hi:[1,0,1]
	v_pk_fma_f32 v[86:87], v[38:39], v[174:175], v[234:235] op_sel_hi:[1,0,1]
	ds_write_b64 v1, v[160:161] offset:54016
	s_waitcnt lgkmcnt(9)
	v_pk_mul_f32 v[164:165], v[72:73], v[176:177]
	ds_read_b128 v[208:211], v2 offset:16896
	v_pk_mul_f32 v[166:167], v[80:81], v[176:177]
	ds_read_b128 v[212:215], v2 offset:16912
	v_pk_mul_f32 v[168:169], v[72:73], v[48:49]
	ds_read_b128 v[4:7], v2 offset:4864
	v_pk_mul_f32 v[170:171], v[80:81], v[48:49]
	ds_read_b128 v[8:11], v2 offset:4880
	v_pk_fma_f32 v[164:165], v[74:75], v[178:179], v[164:165]
	ds_read_b128 v[40:43], v2 offset:13056
	v_pk_fma_f32 v[166:167], v[82:83], v[178:179], v[166:167]
	ds_read_b128 v[44:47], v2 offset:13072
	v_pk_fma_f32 v[168:169], v[74:75], v[50:51], v[168:169]
	ds_read_b64 v[26:27], v3 offset:41728
	v_pk_fma_f32 v[170:171], v[82:83], v[50:51], v[170:171]
	ds_read_b128 v[12:15], v2 offset:768
	s_waitcnt lgkmcnt(15)
	v_pk_fma_f32 v[164:165], v[76:77], v[180:181], v[164:165]
	ds_read_b128 v[28:31], v2 offset:784
	v_pk_fma_f32 v[166:167], v[84:85], v[180:181], v[166:167]
	ds_read_b128 v[32:35], v2 offset:8960
	v_pk_fma_f32 v[168:169], v[76:77], v[52:53], v[168:169]
	ds_read_b128 v[36:39], v2 offset:8976
	v_pk_fma_f32 v[170:171], v[84:85], v[52:53], v[170:171]
	v_pk_fma_f32 v[164:165], v[78:79], v[182:183], v[164:165]
	v_pk_fma_f32 v[166:167], v[86:87], v[182:183], v[166:167]
	v_pk_fma_f32 v[168:169], v[78:79], v[54:55], v[168:169]
	v_pk_fma_f32 v[170:171], v[86:87], v[54:55], v[170:171]
	s_waitcnt lgkmcnt(15)
	v_pk_mul_f32 v[218:219], v[216:217], v[200:201] op_sel_hi:[0,1]
	v_pk_mul_f32 v[226:227], v[216:217], v[200:201] op_sel:[1,0]
	v_pk_mul_f32 v[220:221], v[216:217], v[202:203] op_sel_hi:[0,1]
	v_pk_mul_f32 v[228:229], v[216:217], v[202:203] op_sel:[1,0]
	v_pk_mul_f32 v[222:223], v[216:217], v[204:205] op_sel_hi:[0,1]
	v_pk_mul_f32 v[230:231], v[216:217], v[204:205] op_sel:[1,0]
	v_pk_mul_f32 v[224:225], v[216:217], v[206:207] op_sel_hi:[0,1]
	v_pk_mul_f32 v[234:235], v[216:217], v[206:207] op_sel:[1,0]
	v_add_f32_e32 v172, v164, v165
	v_add_f32_e32 v174, v166, v167
	v_add_f32_e32 v160, v168, v169
	v_add_f32_e32 v161, v170, v171
	s_waitcnt lgkmcnt(15)
	v_pk_fma_f32 v[218:219], v[72:73], v[184:185], v[218:219]
	v_pk_fma_f32 v[226:227], v[80:81], v[184:185], v[226:227]
	v_pk_fma_f32 v[220:221], v[74:75], v[186:187], v[220:221]
	v_pk_fma_f32 v[228:229], v[82:83], v[186:187], v[228:229]
	v_add_f32_dpp v172, v172, v172 quad_perm:[1,0,3,2] row_mask:0xf bank_mask:0xf bound_ctrl:1
	v_add_f32_dpp v174, v174, v174 quad_perm:[1,0,3,2] row_mask:0xf bank_mask:0xf bound_ctrl:1
	v_add_f32_dpp v160, v160, v160 quad_perm:[1,0,3,2] row_mask:0xf bank_mask:0xf bound_ctrl:1
	v_add_f32_dpp v161, v161, v161 quad_perm:[1,0,3,2] row_mask:0xf bank_mask:0xf bound_ctrl:1
	s_waitcnt lgkmcnt(14)
	v_pk_fma_f32 v[222:223], v[76:77], v[188:189], v[222:223]
	v_pk_fma_f32 v[230:231], v[84:85], v[188:189], v[230:231]
	v_pk_fma_f32 v[224:225], v[78:79], v[190:191], v[224:225]
	v_pk_fma_f32 v[234:235], v[86:87], v[190:191], v[234:235]
	v_add_f32_dpp v172, v172, v172 quad_perm:[2,3,0,1] row_mask:0xf bank_mask:0xf bound_ctrl:1
	v_add_f32_dpp v174, v174, v174 quad_perm:[2,3,0,1] row_mask:0xf bank_mask:0xf bound_ctrl:1
	v_add_f32_dpp v160, v160, v160 quad_perm:[2,3,0,1] row_mask:0xf bank_mask:0xf bound_ctrl:1
	v_add_f32_dpp v161, v161, v161 quad_perm:[2,3,0,1] row_mask:0xf bank_mask:0xf bound_ctrl:1
	v_add_f32_dpp v172, v172, v172 row_half_mirror row_mask:0xf bank_mask:0xf bound_ctrl:1
	v_add_f32_dpp v174, v174, v174 row_half_mirror row_mask:0xf bank_mask:0xf bound_ctrl:1
	v_add_f32_dpp v160, v160, v160 row_half_mirror row_mask:0xf bank_mask:0xf bound_ctrl:1
	v_add_f32_dpp v161, v161, v161 row_half_mirror row_mask:0xf bank_mask:0xf bound_ctrl:1
	s_waitcnt lgkmcnt(13)
	v_pk_fma_f32 v[72:73], v[192:193], v[172:173], v[218:219] op_sel_hi:[1,0,1]
	v_pk_fma_f32 v[80:81], v[192:193], v[174:175], v[226:227] op_sel_hi:[1,0,1]
	v_pk_fma_f32 v[74:75], v[194:195], v[172:173], v[220:221] op_sel_hi:[1,0,1]
	v_pk_fma_f32 v[82:83], v[194:195], v[174:175], v[228:229] op_sel_hi:[1,0,1]
	s_waitcnt lgkmcnt(12)
	v_pk_fma_f32 v[76:77], v[196:197], v[172:173], v[222:223] op_sel_hi:[1,0,1]
	v_pk_fma_f32 v[84:85], v[196:197], v[174:175], v[230:231] op_sel_hi:[1,0,1]
	v_pk_fma_f32 v[78:79], v[198:199], v[172:173], v[224:225] op_sel_hi:[1,0,1]
	v_pk_fma_f32 v[86:87], v[198:199], v[174:175], v[234:235] op_sel_hi:[1,0,1]
	ds_write_b64 v1, v[160:161] offset:54272
	s_waitcnt lgkmcnt(9)
	v_pk_mul_f32 v[164:165], v[72:73], v[4:5]
	ds_read_b128 v[48:51], v2 offset:17152
	v_pk_mul_f32 v[166:167], v[80:81], v[4:5]
	ds_read_b128 v[52:55], v2 offset:17168
	v_pk_mul_f32 v[168:169], v[72:73], v[208:209]
	ds_read_b128 v[176:179], v2 offset:5120
	v_pk_mul_f32 v[170:171], v[80:81], v[208:209]
	ds_read_b128 v[180:183], v2 offset:5136
	v_pk_fma_f32 v[164:165], v[74:75], v[6:7], v[164:165]
	ds_read_b128 v[200:203], v2 offset:13312
	v_pk_fma_f32 v[166:167], v[82:83], v[6:7], v[166:167]
	ds_read_b128 v[204:207], v2 offset:13328
	v_pk_fma_f32 v[168:169], v[74:75], v[210:211], v[168:169]
	ds_read_b64 v[216:217], v3 offset:41984
	v_pk_fma_f32 v[170:171], v[82:83], v[210:211], v[170:171]
	ds_read_b128 v[184:187], v2 offset:1024
	s_waitcnt lgkmcnt(15)
	v_pk_fma_f32 v[164:165], v[76:77], v[8:9], v[164:165]
	ds_read_b128 v[188:191], v2 offset:1040
	v_pk_fma_f32 v[166:167], v[84:85], v[8:9], v[166:167]
	ds_read_b128 v[192:195], v2 offset:9216
	v_pk_fma_f32 v[168:169], v[76:77], v[212:213], v[168:169]
	ds_read_b128 v[196:199], v2 offset:9232
	v_pk_fma_f32 v[170:171], v[84:85], v[212:213], v[170:171]
	v_pk_fma_f32 v[164:165], v[78:79], v[10:11], v[164:165]
	v_pk_fma_f32 v[166:167], v[86:87], v[10:11], v[166:167]
	v_pk_fma_f32 v[168:169], v[78:79], v[214:215], v[168:169]
	v_pk_fma_f32 v[170:171], v[86:87], v[214:215], v[170:171]
	s_waitcnt lgkmcnt(15)
	v_pk_mul_f32 v[218:219], v[26:27], v[40:41] op_sel_hi:[0,1]
	v_pk_mul_f32 v[226:227], v[26:27], v[40:41] op_sel:[1,0]
	v_pk_mul_f32 v[220:221], v[26:27], v[42:43] op_sel_hi:[0,1]
	v_pk_mul_f32 v[228:229], v[26:27], v[42:43] op_sel:[1,0]
	v_pk_mul_f32 v[222:223], v[26:27], v[44:45] op_sel_hi:[0,1]
	v_pk_mul_f32 v[230:231], v[26:27], v[44:45] op_sel:[1,0]
	v_pk_mul_f32 v[224:225], v[26:27], v[46:47] op_sel_hi:[0,1]
	v_pk_mul_f32 v[234:235], v[26:27], v[46:47] op_sel:[1,0]
	v_add_f32_e32 v172, v164, v165
	v_add_f32_e32 v174, v166, v167
	v_add_f32_e32 v160, v168, v169
	v_add_f32_e32 v161, v170, v171
	s_waitcnt lgkmcnt(15)
	v_pk_fma_f32 v[218:219], v[72:73], v[12:13], v[218:219]
	v_pk_fma_f32 v[226:227], v[80:81], v[12:13], v[226:227]
	v_pk_fma_f32 v[220:221], v[74:75], v[14:15], v[220:221]
	v_pk_fma_f32 v[228:229], v[82:83], v[14:15], v[228:229]
	v_add_f32_dpp v172, v172, v172 quad_perm:[1,0,3,2] row_mask:0xf bank_mask:0xf bound_ctrl:1
	v_add_f32_dpp v174, v174, v174 quad_perm:[1,0,3,2] row_mask:0xf bank_mask:0xf bound_ctrl:1
	v_add_f32_dpp v160, v160, v160 quad_perm:[1,0,3,2] row_mask:0xf bank_mask:0xf bound_ctrl:1
	v_add_f32_dpp v161, v161, v161 quad_perm:[1,0,3,2] row_mask:0xf bank_mask:0xf bound_ctrl:1
	s_waitcnt lgkmcnt(14)
	v_pk_fma_f32 v[222:223], v[76:77], v[28:29], v[222:223]
	v_pk_fma_f32 v[230:231], v[84:85], v[28:29], v[230:231]
	v_pk_fma_f32 v[224:225], v[78:79], v[30:31], v[224:225]
	v_pk_fma_f32 v[234:235], v[86:87], v[30:31], v[234:235]
	v_add_f32_dpp v172, v172, v172 quad_perm:[2,3,0,1] row_mask:0xf bank_mask:0xf bound_ctrl:1
	v_add_f32_dpp v174, v174, v174 quad_perm:[2,3,0,1] row_mask:0xf bank_mask:0xf bound_ctrl:1
	v_add_f32_dpp v160, v160, v160 quad_perm:[2,3,0,1] row_mask:0xf bank_mask:0xf bound_ctrl:1
	v_add_f32_dpp v161, v161, v161 quad_perm:[2,3,0,1] row_mask:0xf bank_mask:0xf bound_ctrl:1
	v_add_f32_dpp v172, v172, v172 row_half_mirror row_mask:0xf bank_mask:0xf bound_ctrl:1
	v_add_f32_dpp v174, v174, v174 row_half_mirror row_mask:0xf bank_mask:0xf bound_ctrl:1
	v_add_f32_dpp v160, v160, v160 row_half_mirror row_mask:0xf bank_mask:0xf bound_ctrl:1
	v_add_f32_dpp v161, v161, v161 row_half_mirror row_mask:0xf bank_mask:0xf bound_ctrl:1
	s_waitcnt lgkmcnt(13)
	v_pk_fma_f32 v[72:73], v[32:33], v[172:173], v[218:219] op_sel_hi:[1,0,1]
	v_pk_fma_f32 v[80:81], v[32:33], v[174:175], v[226:227] op_sel_hi:[1,0,1]
	v_pk_fma_f32 v[74:75], v[34:35], v[172:173], v[220:221] op_sel_hi:[1,0,1]
	v_pk_fma_f32 v[82:83], v[34:35], v[174:175], v[228:229] op_sel_hi:[1,0,1]
	s_waitcnt lgkmcnt(12)
	v_pk_fma_f32 v[76:77], v[36:37], v[172:173], v[222:223] op_sel_hi:[1,0,1]
	v_pk_fma_f32 v[84:85], v[36:37], v[174:175], v[230:231] op_sel_hi:[1,0,1]
	v_pk_fma_f32 v[78:79], v[38:39], v[172:173], v[224:225] op_sel_hi:[1,0,1]
	v_pk_fma_f32 v[86:87], v[38:39], v[174:175], v[234:235] op_sel_hi:[1,0,1]
	ds_write_b64 v1, v[160:161] offset:54528
	s_waitcnt lgkmcnt(9)
	v_pk_mul_f32 v[164:165], v[72:73], v[176:177]
	ds_read_b128 v[208:211], v2 offset:17408
	v_pk_mul_f32 v[166:167], v[80:81], v[176:177]
	ds_read_b128 v[212:215], v2 offset:17424
	v_pk_mul_f32 v[168:169], v[72:73], v[48:49]
	ds_read_b128 v[4:7], v2 offset:5376
	v_pk_mul_f32 v[170:171], v[80:81], v[48:49]
	ds_read_b128 v[8:11], v2 offset:5392
	v_pk_fma_f32 v[164:165], v[74:75], v[178:179], v[164:165]
	ds_read_b128 v[40:43], v2 offset:13568
	v_pk_fma_f32 v[166:167], v[82:83], v[178:179], v[166:167]
	ds_read_b128 v[44:47], v2 offset:13584
	v_pk_fma_f32 v[168:169], v[74:75], v[50:51], v[168:169]
	ds_read_b64 v[26:27], v3 offset:42240
	v_pk_fma_f32 v[170:171], v[82:83], v[50:51], v[170:171]
	ds_read_b128 v[12:15], v2 offset:1280
	s_waitcnt lgkmcnt(15)
	v_pk_fma_f32 v[164:165], v[76:77], v[180:181], v[164:165]
	ds_read_b128 v[28:31], v2 offset:1296
	v_pk_fma_f32 v[166:167], v[84:85], v[180:181], v[166:167]
	ds_read_b128 v[32:35], v2 offset:9472
	v_pk_fma_f32 v[168:169], v[76:77], v[52:53], v[168:169]
	ds_read_b128 v[36:39], v2 offset:9488
	v_pk_fma_f32 v[170:171], v[84:85], v[52:53], v[170:171]
	v_pk_fma_f32 v[164:165], v[78:79], v[182:183], v[164:165]
	v_pk_fma_f32 v[166:167], v[86:87], v[182:183], v[166:167]
	v_pk_fma_f32 v[168:169], v[78:79], v[54:55], v[168:169]
	v_pk_fma_f32 v[170:171], v[86:87], v[54:55], v[170:171]
	s_waitcnt lgkmcnt(15)
	v_pk_mul_f32 v[218:219], v[216:217], v[200:201] op_sel_hi:[0,1]
	v_pk_mul_f32 v[226:227], v[216:217], v[200:201] op_sel:[1,0]
	v_pk_mul_f32 v[220:221], v[216:217], v[202:203] op_sel_hi:[0,1]
	v_pk_mul_f32 v[228:229], v[216:217], v[202:203] op_sel:[1,0]
	v_pk_mul_f32 v[222:223], v[216:217], v[204:205] op_sel_hi:[0,1]
	v_pk_mul_f32 v[230:231], v[216:217], v[204:205] op_sel:[1,0]
	v_pk_mul_f32 v[224:225], v[216:217], v[206:207] op_sel_hi:[0,1]
	v_pk_mul_f32 v[234:235], v[216:217], v[206:207] op_sel:[1,0]
	v_add_f32_e32 v172, v164, v165
	v_add_f32_e32 v174, v166, v167
	v_add_f32_e32 v160, v168, v169
	v_add_f32_e32 v161, v170, v171
	s_waitcnt lgkmcnt(15)
	v_pk_fma_f32 v[218:219], v[72:73], v[184:185], v[218:219]
	v_pk_fma_f32 v[226:227], v[80:81], v[184:185], v[226:227]
	v_pk_fma_f32 v[220:221], v[74:75], v[186:187], v[220:221]
	v_pk_fma_f32 v[228:229], v[82:83], v[186:187], v[228:229]
	v_add_f32_dpp v172, v172, v172 quad_perm:[1,0,3,2] row_mask:0xf bank_mask:0xf bound_ctrl:1
	v_add_f32_dpp v174, v174, v174 quad_perm:[1,0,3,2] row_mask:0xf bank_mask:0xf bound_ctrl:1
	v_add_f32_dpp v160, v160, v160 quad_perm:[1,0,3,2] row_mask:0xf bank_mask:0xf bound_ctrl:1
	v_add_f32_dpp v161, v161, v161 quad_perm:[1,0,3,2] row_mask:0xf bank_mask:0xf bound_ctrl:1
	s_waitcnt lgkmcnt(14)
	v_pk_fma_f32 v[222:223], v[76:77], v[188:189], v[222:223]
	v_pk_fma_f32 v[230:231], v[84:85], v[188:189], v[230:231]
	v_pk_fma_f32 v[224:225], v[78:79], v[190:191], v[224:225]
	v_pk_fma_f32 v[234:235], v[86:87], v[190:191], v[234:235]
	v_add_f32_dpp v172, v172, v172 quad_perm:[2,3,0,1] row_mask:0xf bank_mask:0xf bound_ctrl:1
	v_add_f32_dpp v174, v174, v174 quad_perm:[2,3,0,1] row_mask:0xf bank_mask:0xf bound_ctrl:1
	v_add_f32_dpp v160, v160, v160 quad_perm:[2,3,0,1] row_mask:0xf bank_mask:0xf bound_ctrl:1
	v_add_f32_dpp v161, v161, v161 quad_perm:[2,3,0,1] row_mask:0xf bank_mask:0xf bound_ctrl:1
	v_add_f32_dpp v172, v172, v172 row_half_mirror row_mask:0xf bank_mask:0xf bound_ctrl:1
	v_add_f32_dpp v174, v174, v174 row_half_mirror row_mask:0xf bank_mask:0xf bound_ctrl:1
	v_add_f32_dpp v160, v160, v160 row_half_mirror row_mask:0xf bank_mask:0xf bound_ctrl:1
	v_add_f32_dpp v161, v161, v161 row_half_mirror row_mask:0xf bank_mask:0xf bound_ctrl:1
	s_waitcnt lgkmcnt(13)
	v_pk_fma_f32 v[72:73], v[192:193], v[172:173], v[218:219] op_sel_hi:[1,0,1]
	v_pk_fma_f32 v[80:81], v[192:193], v[174:175], v[226:227] op_sel_hi:[1,0,1]
	v_pk_fma_f32 v[74:75], v[194:195], v[172:173], v[220:221] op_sel_hi:[1,0,1]
	v_pk_fma_f32 v[82:83], v[194:195], v[174:175], v[228:229] op_sel_hi:[1,0,1]
	s_waitcnt lgkmcnt(12)
	v_pk_fma_f32 v[76:77], v[196:197], v[172:173], v[222:223] op_sel_hi:[1,0,1]
	v_pk_fma_f32 v[84:85], v[196:197], v[174:175], v[230:231] op_sel_hi:[1,0,1]
	v_pk_fma_f32 v[78:79], v[198:199], v[172:173], v[224:225] op_sel_hi:[1,0,1]
	v_pk_fma_f32 v[86:87], v[198:199], v[174:175], v[234:235] op_sel_hi:[1,0,1]
	ds_write_b64 v1, v[160:161] offset:54784
	s_waitcnt lgkmcnt(9)
	v_pk_mul_f32 v[164:165], v[72:73], v[4:5]
	ds_read_b128 v[48:51], v2 offset:17664
	v_pk_mul_f32 v[166:167], v[80:81], v[4:5]
	ds_read_b128 v[52:55], v2 offset:17680
	v_pk_mul_f32 v[168:169], v[72:73], v[208:209]
	ds_read_b128 v[176:179], v2 offset:5632
	v_pk_mul_f32 v[170:171], v[80:81], v[208:209]
	ds_read_b128 v[180:183], v2 offset:5648
	v_pk_fma_f32 v[164:165], v[74:75], v[6:7], v[164:165]
	ds_read_b128 v[200:203], v2 offset:13824
	v_pk_fma_f32 v[166:167], v[82:83], v[6:7], v[166:167]
	ds_read_b128 v[204:207], v2 offset:13840
	v_pk_fma_f32 v[168:169], v[74:75], v[210:211], v[168:169]
	ds_read_b64 v[216:217], v3 offset:42496
	v_pk_fma_f32 v[170:171], v[82:83], v[210:211], v[170:171]
	ds_read_b128 v[184:187], v2 offset:1536
	s_waitcnt lgkmcnt(15)
	v_pk_fma_f32 v[164:165], v[76:77], v[8:9], v[164:165]
	ds_read_b128 v[188:191], v2 offset:1552
	v_pk_fma_f32 v[166:167], v[84:85], v[8:9], v[166:167]
	ds_read_b128 v[192:195], v2 offset:9728
	v_pk_fma_f32 v[168:169], v[76:77], v[212:213], v[168:169]
	ds_read_b128 v[196:199], v2 offset:9744
	v_pk_fma_f32 v[170:171], v[84:85], v[212:213], v[170:171]
	v_pk_fma_f32 v[164:165], v[78:79], v[10:11], v[164:165]
	v_pk_fma_f32 v[166:167], v[86:87], v[10:11], v[166:167]
	v_pk_fma_f32 v[168:169], v[78:79], v[214:215], v[168:169]
	v_pk_fma_f32 v[170:171], v[86:87], v[214:215], v[170:171]
	s_waitcnt lgkmcnt(15)
	v_pk_mul_f32 v[218:219], v[26:27], v[40:41] op_sel_hi:[0,1]
	v_pk_mul_f32 v[226:227], v[26:27], v[40:41] op_sel:[1,0]
	v_pk_mul_f32 v[220:221], v[26:27], v[42:43] op_sel_hi:[0,1]
	v_pk_mul_f32 v[228:229], v[26:27], v[42:43] op_sel:[1,0]
	v_pk_mul_f32 v[222:223], v[26:27], v[44:45] op_sel_hi:[0,1]
	v_pk_mul_f32 v[230:231], v[26:27], v[44:45] op_sel:[1,0]
	v_pk_mul_f32 v[224:225], v[26:27], v[46:47] op_sel_hi:[0,1]
	v_pk_mul_f32 v[234:235], v[26:27], v[46:47] op_sel:[1,0]
	v_add_f32_e32 v172, v164, v165
	v_add_f32_e32 v174, v166, v167
	v_add_f32_e32 v160, v168, v169
	v_add_f32_e32 v161, v170, v171
	s_waitcnt lgkmcnt(15)
	v_pk_fma_f32 v[218:219], v[72:73], v[12:13], v[218:219]
	v_pk_fma_f32 v[226:227], v[80:81], v[12:13], v[226:227]
	v_pk_fma_f32 v[220:221], v[74:75], v[14:15], v[220:221]
	v_pk_fma_f32 v[228:229], v[82:83], v[14:15], v[228:229]
	v_add_f32_dpp v172, v172, v172 quad_perm:[1,0,3,2] row_mask:0xf bank_mask:0xf bound_ctrl:1
	v_add_f32_dpp v174, v174, v174 quad_perm:[1,0,3,2] row_mask:0xf bank_mask:0xf bound_ctrl:1
	v_add_f32_dpp v160, v160, v160 quad_perm:[1,0,3,2] row_mask:0xf bank_mask:0xf bound_ctrl:1
	v_add_f32_dpp v161, v161, v161 quad_perm:[1,0,3,2] row_mask:0xf bank_mask:0xf bound_ctrl:1
	s_waitcnt lgkmcnt(14)
	v_pk_fma_f32 v[222:223], v[76:77], v[28:29], v[222:223]
	v_pk_fma_f32 v[230:231], v[84:85], v[28:29], v[230:231]
	v_pk_fma_f32 v[224:225], v[78:79], v[30:31], v[224:225]
	v_pk_fma_f32 v[234:235], v[86:87], v[30:31], v[234:235]
	v_add_f32_dpp v172, v172, v172 quad_perm:[2,3,0,1] row_mask:0xf bank_mask:0xf bound_ctrl:1
	v_add_f32_dpp v174, v174, v174 quad_perm:[2,3,0,1] row_mask:0xf bank_mask:0xf bound_ctrl:1
	v_add_f32_dpp v160, v160, v160 quad_perm:[2,3,0,1] row_mask:0xf bank_mask:0xf bound_ctrl:1
	v_add_f32_dpp v161, v161, v161 quad_perm:[2,3,0,1] row_mask:0xf bank_mask:0xf bound_ctrl:1
	v_add_f32_dpp v172, v172, v172 row_half_mirror row_mask:0xf bank_mask:0xf bound_ctrl:1
	v_add_f32_dpp v174, v174, v174 row_half_mirror row_mask:0xf bank_mask:0xf bound_ctrl:1
	v_add_f32_dpp v160, v160, v160 row_half_mirror row_mask:0xf bank_mask:0xf bound_ctrl:1
	v_add_f32_dpp v161, v161, v161 row_half_mirror row_mask:0xf bank_mask:0xf bound_ctrl:1
	s_waitcnt lgkmcnt(13)
	v_pk_fma_f32 v[72:73], v[32:33], v[172:173], v[218:219] op_sel_hi:[1,0,1]
	v_pk_fma_f32 v[80:81], v[32:33], v[174:175], v[226:227] op_sel_hi:[1,0,1]
	v_pk_fma_f32 v[74:75], v[34:35], v[172:173], v[220:221] op_sel_hi:[1,0,1]
	v_pk_fma_f32 v[82:83], v[34:35], v[174:175], v[228:229] op_sel_hi:[1,0,1]
	s_waitcnt lgkmcnt(12)
	v_pk_fma_f32 v[76:77], v[36:37], v[172:173], v[222:223] op_sel_hi:[1,0,1]
	v_pk_fma_f32 v[84:85], v[36:37], v[174:175], v[230:231] op_sel_hi:[1,0,1]
	v_pk_fma_f32 v[78:79], v[38:39], v[172:173], v[224:225] op_sel_hi:[1,0,1]
	v_pk_fma_f32 v[86:87], v[38:39], v[174:175], v[234:235] op_sel_hi:[1,0,1]
	ds_write_b64 v1, v[160:161] offset:55040
	s_waitcnt lgkmcnt(9)
	v_pk_mul_f32 v[164:165], v[72:73], v[176:177]
	ds_read_b128 v[208:211], v2 offset:17920
	v_pk_mul_f32 v[166:167], v[80:81], v[176:177]
	ds_read_b128 v[212:215], v2 offset:17936
	v_pk_mul_f32 v[168:169], v[72:73], v[48:49]
	ds_read_b128 v[4:7], v2 offset:5888
	v_pk_mul_f32 v[170:171], v[80:81], v[48:49]
	ds_read_b128 v[8:11], v2 offset:5904
	v_pk_fma_f32 v[164:165], v[74:75], v[178:179], v[164:165]
	ds_read_b128 v[40:43], v2 offset:14080
	v_pk_fma_f32 v[166:167], v[82:83], v[178:179], v[166:167]
	ds_read_b128 v[44:47], v2 offset:14096
	v_pk_fma_f32 v[168:169], v[74:75], v[50:51], v[168:169]
	ds_read_b64 v[26:27], v3 offset:42752
	v_pk_fma_f32 v[170:171], v[82:83], v[50:51], v[170:171]
	ds_read_b128 v[12:15], v2 offset:1792
	s_waitcnt lgkmcnt(15)
	v_pk_fma_f32 v[164:165], v[76:77], v[180:181], v[164:165]
	ds_read_b128 v[28:31], v2 offset:1808
	v_pk_fma_f32 v[166:167], v[84:85], v[180:181], v[166:167]
	ds_read_b128 v[32:35], v2 offset:9984
	v_pk_fma_f32 v[168:169], v[76:77], v[52:53], v[168:169]
	ds_read_b128 v[36:39], v2 offset:10000
	v_pk_fma_f32 v[170:171], v[84:85], v[52:53], v[170:171]
	v_pk_fma_f32 v[164:165], v[78:79], v[182:183], v[164:165]
	v_pk_fma_f32 v[166:167], v[86:87], v[182:183], v[166:167]
	v_pk_fma_f32 v[168:169], v[78:79], v[54:55], v[168:169]
	v_pk_fma_f32 v[170:171], v[86:87], v[54:55], v[170:171]
	s_waitcnt lgkmcnt(15)
	v_pk_mul_f32 v[218:219], v[216:217], v[200:201] op_sel_hi:[0,1]
	v_pk_mul_f32 v[226:227], v[216:217], v[200:201] op_sel:[1,0]
	v_pk_mul_f32 v[220:221], v[216:217], v[202:203] op_sel_hi:[0,1]
	v_pk_mul_f32 v[228:229], v[216:217], v[202:203] op_sel:[1,0]
	v_pk_mul_f32 v[222:223], v[216:217], v[204:205] op_sel_hi:[0,1]
	v_pk_mul_f32 v[230:231], v[216:217], v[204:205] op_sel:[1,0]
	v_pk_mul_f32 v[224:225], v[216:217], v[206:207] op_sel_hi:[0,1]
	v_pk_mul_f32 v[234:235], v[216:217], v[206:207] op_sel:[1,0]
	v_add_f32_e32 v172, v164, v165
	v_add_f32_e32 v174, v166, v167
	v_add_f32_e32 v160, v168, v169
	v_add_f32_e32 v161, v170, v171
	s_waitcnt lgkmcnt(15)
	v_pk_fma_f32 v[218:219], v[72:73], v[184:185], v[218:219]
	v_pk_fma_f32 v[226:227], v[80:81], v[184:185], v[226:227]
	v_pk_fma_f32 v[220:221], v[74:75], v[186:187], v[220:221]
	v_pk_fma_f32 v[228:229], v[82:83], v[186:187], v[228:229]
	v_add_f32_dpp v172, v172, v172 quad_perm:[1,0,3,2] row_mask:0xf bank_mask:0xf bound_ctrl:1
	v_add_f32_dpp v174, v174, v174 quad_perm:[1,0,3,2] row_mask:0xf bank_mask:0xf bound_ctrl:1
	v_add_f32_dpp v160, v160, v160 quad_perm:[1,0,3,2] row_mask:0xf bank_mask:0xf bound_ctrl:1
	v_add_f32_dpp v161, v161, v161 quad_perm:[1,0,3,2] row_mask:0xf bank_mask:0xf bound_ctrl:1
	s_waitcnt lgkmcnt(14)
	v_pk_fma_f32 v[222:223], v[76:77], v[188:189], v[222:223]
	v_pk_fma_f32 v[230:231], v[84:85], v[188:189], v[230:231]
	v_pk_fma_f32 v[224:225], v[78:79], v[190:191], v[224:225]
	v_pk_fma_f32 v[234:235], v[86:87], v[190:191], v[234:235]
	v_add_f32_dpp v172, v172, v172 quad_perm:[2,3,0,1] row_mask:0xf bank_mask:0xf bound_ctrl:1
	v_add_f32_dpp v174, v174, v174 quad_perm:[2,3,0,1] row_mask:0xf bank_mask:0xf bound_ctrl:1
	v_add_f32_dpp v160, v160, v160 quad_perm:[2,3,0,1] row_mask:0xf bank_mask:0xf bound_ctrl:1
	v_add_f32_dpp v161, v161, v161 quad_perm:[2,3,0,1] row_mask:0xf bank_mask:0xf bound_ctrl:1
	v_add_f32_dpp v172, v172, v172 row_half_mirror row_mask:0xf bank_mask:0xf bound_ctrl:1
	v_add_f32_dpp v174, v174, v174 row_half_mirror row_mask:0xf bank_mask:0xf bound_ctrl:1
	v_add_f32_dpp v160, v160, v160 row_half_mirror row_mask:0xf bank_mask:0xf bound_ctrl:1
	v_add_f32_dpp v161, v161, v161 row_half_mirror row_mask:0xf bank_mask:0xf bound_ctrl:1
	s_waitcnt lgkmcnt(13)
	v_pk_fma_f32 v[72:73], v[192:193], v[172:173], v[218:219] op_sel_hi:[1,0,1]
	v_pk_fma_f32 v[80:81], v[192:193], v[174:175], v[226:227] op_sel_hi:[1,0,1]
	v_pk_fma_f32 v[74:75], v[194:195], v[172:173], v[220:221] op_sel_hi:[1,0,1]
	v_pk_fma_f32 v[82:83], v[194:195], v[174:175], v[228:229] op_sel_hi:[1,0,1]
	s_waitcnt lgkmcnt(12)
	v_pk_fma_f32 v[76:77], v[196:197], v[172:173], v[222:223] op_sel_hi:[1,0,1]
	v_pk_fma_f32 v[84:85], v[196:197], v[174:175], v[230:231] op_sel_hi:[1,0,1]
	v_pk_fma_f32 v[78:79], v[198:199], v[172:173], v[224:225] op_sel_hi:[1,0,1]
	v_pk_fma_f32 v[86:87], v[198:199], v[174:175], v[234:235] op_sel_hi:[1,0,1]
	ds_write_b64 v1, v[160:161] offset:55296
	s_waitcnt lgkmcnt(9)
	v_pk_mul_f32 v[164:165], v[72:73], v[4:5]
	ds_read_b128 v[48:51], v2 offset:18176
	v_pk_mul_f32 v[166:167], v[80:81], v[4:5]
	ds_read_b128 v[52:55], v2 offset:18192
	v_pk_mul_f32 v[168:169], v[72:73], v[208:209]
	ds_read_b128 v[176:179], v2 offset:6144
	v_pk_mul_f32 v[170:171], v[80:81], v[208:209]
	ds_read_b128 v[180:183], v2 offset:6160
	v_pk_fma_f32 v[164:165], v[74:75], v[6:7], v[164:165]
	ds_read_b128 v[200:203], v2 offset:14336
	v_pk_fma_f32 v[166:167], v[82:83], v[6:7], v[166:167]
	ds_read_b128 v[204:207], v2 offset:14352
	v_pk_fma_f32 v[168:169], v[74:75], v[210:211], v[168:169]
	ds_read_b64 v[216:217], v3 offset:43008
	v_pk_fma_f32 v[170:171], v[82:83], v[210:211], v[170:171]
	ds_read_b128 v[184:187], v2 offset:2048
	s_waitcnt lgkmcnt(15)
	v_pk_fma_f32 v[164:165], v[76:77], v[8:9], v[164:165]
	ds_read_b128 v[188:191], v2 offset:2064
	v_pk_fma_f32 v[166:167], v[84:85], v[8:9], v[166:167]
	ds_read_b128 v[192:195], v2 offset:10240
	v_pk_fma_f32 v[168:169], v[76:77], v[212:213], v[168:169]
	ds_read_b128 v[196:199], v2 offset:10256
	v_pk_fma_f32 v[170:171], v[84:85], v[212:213], v[170:171]
	v_pk_fma_f32 v[164:165], v[78:79], v[10:11], v[164:165]
	v_pk_fma_f32 v[166:167], v[86:87], v[10:11], v[166:167]
	v_pk_fma_f32 v[168:169], v[78:79], v[214:215], v[168:169]
	v_pk_fma_f32 v[170:171], v[86:87], v[214:215], v[170:171]
	s_waitcnt lgkmcnt(15)
	v_pk_mul_f32 v[218:219], v[26:27], v[40:41] op_sel_hi:[0,1]
	v_pk_mul_f32 v[226:227], v[26:27], v[40:41] op_sel:[1,0]
	v_pk_mul_f32 v[220:221], v[26:27], v[42:43] op_sel_hi:[0,1]
	v_pk_mul_f32 v[228:229], v[26:27], v[42:43] op_sel:[1,0]
	v_pk_mul_f32 v[222:223], v[26:27], v[44:45] op_sel_hi:[0,1]
	v_pk_mul_f32 v[230:231], v[26:27], v[44:45] op_sel:[1,0]
	v_pk_mul_f32 v[224:225], v[26:27], v[46:47] op_sel_hi:[0,1]
	v_pk_mul_f32 v[234:235], v[26:27], v[46:47] op_sel:[1,0]
	v_add_f32_e32 v172, v164, v165
	v_add_f32_e32 v174, v166, v167
	v_add_f32_e32 v160, v168, v169
	v_add_f32_e32 v161, v170, v171
	s_waitcnt lgkmcnt(15)
	v_pk_fma_f32 v[218:219], v[72:73], v[12:13], v[218:219]
	v_pk_fma_f32 v[226:227], v[80:81], v[12:13], v[226:227]
	v_pk_fma_f32 v[220:221], v[74:75], v[14:15], v[220:221]
	v_pk_fma_f32 v[228:229], v[82:83], v[14:15], v[228:229]
	v_add_f32_dpp v172, v172, v172 quad_perm:[1,0,3,2] row_mask:0xf bank_mask:0xf bound_ctrl:1
	v_add_f32_dpp v174, v174, v174 quad_perm:[1,0,3,2] row_mask:0xf bank_mask:0xf bound_ctrl:1
	v_add_f32_dpp v160, v160, v160 quad_perm:[1,0,3,2] row_mask:0xf bank_mask:0xf bound_ctrl:1
	v_add_f32_dpp v161, v161, v161 quad_perm:[1,0,3,2] row_mask:0xf bank_mask:0xf bound_ctrl:1
	s_waitcnt lgkmcnt(14)
	v_pk_fma_f32 v[222:223], v[76:77], v[28:29], v[222:223]
	v_pk_fma_f32 v[230:231], v[84:85], v[28:29], v[230:231]
	v_pk_fma_f32 v[224:225], v[78:79], v[30:31], v[224:225]
	v_pk_fma_f32 v[234:235], v[86:87], v[30:31], v[234:235]
	v_add_f32_dpp v172, v172, v172 quad_perm:[2,3,0,1] row_mask:0xf bank_mask:0xf bound_ctrl:1
	v_add_f32_dpp v174, v174, v174 quad_perm:[2,3,0,1] row_mask:0xf bank_mask:0xf bound_ctrl:1
	v_add_f32_dpp v160, v160, v160 quad_perm:[2,3,0,1] row_mask:0xf bank_mask:0xf bound_ctrl:1
	v_add_f32_dpp v161, v161, v161 quad_perm:[2,3,0,1] row_mask:0xf bank_mask:0xf bound_ctrl:1
	v_add_f32_dpp v172, v172, v172 row_half_mirror row_mask:0xf bank_mask:0xf bound_ctrl:1
	v_add_f32_dpp v174, v174, v174 row_half_mirror row_mask:0xf bank_mask:0xf bound_ctrl:1
	v_add_f32_dpp v160, v160, v160 row_half_mirror row_mask:0xf bank_mask:0xf bound_ctrl:1
	v_add_f32_dpp v161, v161, v161 row_half_mirror row_mask:0xf bank_mask:0xf bound_ctrl:1
	s_waitcnt lgkmcnt(13)
	v_pk_fma_f32 v[72:73], v[32:33], v[172:173], v[218:219] op_sel_hi:[1,0,1]
	v_pk_fma_f32 v[80:81], v[32:33], v[174:175], v[226:227] op_sel_hi:[1,0,1]
	v_pk_fma_f32 v[74:75], v[34:35], v[172:173], v[220:221] op_sel_hi:[1,0,1]
	v_pk_fma_f32 v[82:83], v[34:35], v[174:175], v[228:229] op_sel_hi:[1,0,1]
	s_waitcnt lgkmcnt(12)
	v_pk_fma_f32 v[76:77], v[36:37], v[172:173], v[222:223] op_sel_hi:[1,0,1]
	v_pk_fma_f32 v[84:85], v[36:37], v[174:175], v[230:231] op_sel_hi:[1,0,1]
	v_pk_fma_f32 v[78:79], v[38:39], v[172:173], v[224:225] op_sel_hi:[1,0,1]
	v_pk_fma_f32 v[86:87], v[38:39], v[174:175], v[234:235] op_sel_hi:[1,0,1]
	ds_write_b64 v1, v[160:161] offset:55552
	s_waitcnt lgkmcnt(9)
	v_pk_mul_f32 v[164:165], v[72:73], v[176:177]
	ds_read_b128 v[208:211], v2 offset:18432
	v_pk_mul_f32 v[166:167], v[80:81], v[176:177]
	ds_read_b128 v[212:215], v2 offset:18448
	v_pk_mul_f32 v[168:169], v[72:73], v[48:49]
	ds_read_b128 v[4:7], v2 offset:6400
	v_pk_mul_f32 v[170:171], v[80:81], v[48:49]
	ds_read_b128 v[8:11], v2 offset:6416
	v_pk_fma_f32 v[164:165], v[74:75], v[178:179], v[164:165]
	ds_read_b128 v[40:43], v2 offset:14592
	v_pk_fma_f32 v[166:167], v[82:83], v[178:179], v[166:167]
	ds_read_b128 v[44:47], v2 offset:14608
	v_pk_fma_f32 v[168:169], v[74:75], v[50:51], v[168:169]
	ds_read_b64 v[26:27], v3 offset:43264
	v_pk_fma_f32 v[170:171], v[82:83], v[50:51], v[170:171]
	ds_read_b128 v[12:15], v2 offset:2304
	s_waitcnt lgkmcnt(15)
	v_pk_fma_f32 v[164:165], v[76:77], v[180:181], v[164:165]
	ds_read_b128 v[28:31], v2 offset:2320
	v_pk_fma_f32 v[166:167], v[84:85], v[180:181], v[166:167]
	ds_read_b128 v[32:35], v2 offset:10496
	v_pk_fma_f32 v[168:169], v[76:77], v[52:53], v[168:169]
	ds_read_b128 v[36:39], v2 offset:10512
	v_pk_fma_f32 v[170:171], v[84:85], v[52:53], v[170:171]
	v_pk_fma_f32 v[164:165], v[78:79], v[182:183], v[164:165]
	v_pk_fma_f32 v[166:167], v[86:87], v[182:183], v[166:167]
	v_pk_fma_f32 v[168:169], v[78:79], v[54:55], v[168:169]
	v_pk_fma_f32 v[170:171], v[86:87], v[54:55], v[170:171]
	s_waitcnt lgkmcnt(15)
	v_pk_mul_f32 v[218:219], v[216:217], v[200:201] op_sel_hi:[0,1]
	v_pk_mul_f32 v[226:227], v[216:217], v[200:201] op_sel:[1,0]
	v_pk_mul_f32 v[220:221], v[216:217], v[202:203] op_sel_hi:[0,1]
	v_pk_mul_f32 v[228:229], v[216:217], v[202:203] op_sel:[1,0]
	v_pk_mul_f32 v[222:223], v[216:217], v[204:205] op_sel_hi:[0,1]
	v_pk_mul_f32 v[230:231], v[216:217], v[204:205] op_sel:[1,0]
	v_pk_mul_f32 v[224:225], v[216:217], v[206:207] op_sel_hi:[0,1]
	v_pk_mul_f32 v[234:235], v[216:217], v[206:207] op_sel:[1,0]
	v_add_f32_e32 v172, v164, v165
	v_add_f32_e32 v174, v166, v167
	v_add_f32_e32 v160, v168, v169
	v_add_f32_e32 v161, v170, v171
	s_waitcnt lgkmcnt(15)
	v_pk_fma_f32 v[218:219], v[72:73], v[184:185], v[218:219]
	v_pk_fma_f32 v[226:227], v[80:81], v[184:185], v[226:227]
	v_pk_fma_f32 v[220:221], v[74:75], v[186:187], v[220:221]
	v_pk_fma_f32 v[228:229], v[82:83], v[186:187], v[228:229]
	v_add_f32_dpp v172, v172, v172 quad_perm:[1,0,3,2] row_mask:0xf bank_mask:0xf bound_ctrl:1
	v_add_f32_dpp v174, v174, v174 quad_perm:[1,0,3,2] row_mask:0xf bank_mask:0xf bound_ctrl:1
	v_add_f32_dpp v160, v160, v160 quad_perm:[1,0,3,2] row_mask:0xf bank_mask:0xf bound_ctrl:1
	v_add_f32_dpp v161, v161, v161 quad_perm:[1,0,3,2] row_mask:0xf bank_mask:0xf bound_ctrl:1
	s_waitcnt lgkmcnt(14)
	v_pk_fma_f32 v[222:223], v[76:77], v[188:189], v[222:223]
	v_pk_fma_f32 v[230:231], v[84:85], v[188:189], v[230:231]
	v_pk_fma_f32 v[224:225], v[78:79], v[190:191], v[224:225]
	v_pk_fma_f32 v[234:235], v[86:87], v[190:191], v[234:235]
	v_add_f32_dpp v172, v172, v172 quad_perm:[2,3,0,1] row_mask:0xf bank_mask:0xf bound_ctrl:1
	v_add_f32_dpp v174, v174, v174 quad_perm:[2,3,0,1] row_mask:0xf bank_mask:0xf bound_ctrl:1
	v_add_f32_dpp v160, v160, v160 quad_perm:[2,3,0,1] row_mask:0xf bank_mask:0xf bound_ctrl:1
	v_add_f32_dpp v161, v161, v161 quad_perm:[2,3,0,1] row_mask:0xf bank_mask:0xf bound_ctrl:1
	v_add_f32_dpp v172, v172, v172 row_half_mirror row_mask:0xf bank_mask:0xf bound_ctrl:1
	v_add_f32_dpp v174, v174, v174 row_half_mirror row_mask:0xf bank_mask:0xf bound_ctrl:1
	v_add_f32_dpp v160, v160, v160 row_half_mirror row_mask:0xf bank_mask:0xf bound_ctrl:1
	v_add_f32_dpp v161, v161, v161 row_half_mirror row_mask:0xf bank_mask:0xf bound_ctrl:1
	s_waitcnt lgkmcnt(13)
	v_pk_fma_f32 v[72:73], v[192:193], v[172:173], v[218:219] op_sel_hi:[1,0,1]
	v_pk_fma_f32 v[80:81], v[192:193], v[174:175], v[226:227] op_sel_hi:[1,0,1]
	v_pk_fma_f32 v[74:75], v[194:195], v[172:173], v[220:221] op_sel_hi:[1,0,1]
	v_pk_fma_f32 v[82:83], v[194:195], v[174:175], v[228:229] op_sel_hi:[1,0,1]
	s_waitcnt lgkmcnt(12)
	v_pk_fma_f32 v[76:77], v[196:197], v[172:173], v[222:223] op_sel_hi:[1,0,1]
	v_pk_fma_f32 v[84:85], v[196:197], v[174:175], v[230:231] op_sel_hi:[1,0,1]
	v_pk_fma_f32 v[78:79], v[198:199], v[172:173], v[224:225] op_sel_hi:[1,0,1]
	v_pk_fma_f32 v[86:87], v[198:199], v[174:175], v[234:235] op_sel_hi:[1,0,1]
	ds_write_b64 v1, v[160:161] offset:55808
	s_waitcnt lgkmcnt(9)
	v_pk_mul_f32 v[164:165], v[72:73], v[4:5]
	ds_read_b128 v[48:51], v2 offset:18688
	v_pk_mul_f32 v[166:167], v[80:81], v[4:5]
	ds_read_b128 v[52:55], v2 offset:18704
	v_pk_mul_f32 v[168:169], v[72:73], v[208:209]
	ds_read_b128 v[176:179], v2 offset:6656
	v_pk_mul_f32 v[170:171], v[80:81], v[208:209]
	ds_read_b128 v[180:183], v2 offset:6672
	v_pk_fma_f32 v[164:165], v[74:75], v[6:7], v[164:165]
	ds_read_b128 v[200:203], v2 offset:14848
	v_pk_fma_f32 v[166:167], v[82:83], v[6:7], v[166:167]
	ds_read_b128 v[204:207], v2 offset:14864
	v_pk_fma_f32 v[168:169], v[74:75], v[210:211], v[168:169]
	ds_read_b64 v[216:217], v3 offset:43520
	v_pk_fma_f32 v[170:171], v[82:83], v[210:211], v[170:171]
	ds_read_b128 v[184:187], v2 offset:2560
	s_waitcnt lgkmcnt(15)
	v_pk_fma_f32 v[164:165], v[76:77], v[8:9], v[164:165]
	ds_read_b128 v[188:191], v2 offset:2576
	v_pk_fma_f32 v[166:167], v[84:85], v[8:9], v[166:167]
	ds_read_b128 v[192:195], v2 offset:10752
	v_pk_fma_f32 v[168:169], v[76:77], v[212:213], v[168:169]
	ds_read_b128 v[196:199], v2 offset:10768
	v_pk_fma_f32 v[170:171], v[84:85], v[212:213], v[170:171]
	v_pk_fma_f32 v[164:165], v[78:79], v[10:11], v[164:165]
	v_pk_fma_f32 v[166:167], v[86:87], v[10:11], v[166:167]
	v_pk_fma_f32 v[168:169], v[78:79], v[214:215], v[168:169]
	v_pk_fma_f32 v[170:171], v[86:87], v[214:215], v[170:171]
	s_waitcnt lgkmcnt(15)
	v_pk_mul_f32 v[218:219], v[26:27], v[40:41] op_sel_hi:[0,1]
	v_pk_mul_f32 v[226:227], v[26:27], v[40:41] op_sel:[1,0]
	v_pk_mul_f32 v[220:221], v[26:27], v[42:43] op_sel_hi:[0,1]
	v_pk_mul_f32 v[228:229], v[26:27], v[42:43] op_sel:[1,0]
	v_pk_mul_f32 v[222:223], v[26:27], v[44:45] op_sel_hi:[0,1]
	v_pk_mul_f32 v[230:231], v[26:27], v[44:45] op_sel:[1,0]
	v_pk_mul_f32 v[224:225], v[26:27], v[46:47] op_sel_hi:[0,1]
	v_pk_mul_f32 v[234:235], v[26:27], v[46:47] op_sel:[1,0]
	v_add_f32_e32 v172, v164, v165
	v_add_f32_e32 v174, v166, v167
	v_add_f32_e32 v160, v168, v169
	v_add_f32_e32 v161, v170, v171
	s_waitcnt lgkmcnt(15)
	v_pk_fma_f32 v[218:219], v[72:73], v[12:13], v[218:219]
	v_pk_fma_f32 v[226:227], v[80:81], v[12:13], v[226:227]
	v_pk_fma_f32 v[220:221], v[74:75], v[14:15], v[220:221]
	v_pk_fma_f32 v[228:229], v[82:83], v[14:15], v[228:229]
	v_add_f32_dpp v172, v172, v172 quad_perm:[1,0,3,2] row_mask:0xf bank_mask:0xf bound_ctrl:1
	v_add_f32_dpp v174, v174, v174 quad_perm:[1,0,3,2] row_mask:0xf bank_mask:0xf bound_ctrl:1
	v_add_f32_dpp v160, v160, v160 quad_perm:[1,0,3,2] row_mask:0xf bank_mask:0xf bound_ctrl:1
	v_add_f32_dpp v161, v161, v161 quad_perm:[1,0,3,2] row_mask:0xf bank_mask:0xf bound_ctrl:1
	s_waitcnt lgkmcnt(14)
	v_pk_fma_f32 v[222:223], v[76:77], v[28:29], v[222:223]
	v_pk_fma_f32 v[230:231], v[84:85], v[28:29], v[230:231]
	v_pk_fma_f32 v[224:225], v[78:79], v[30:31], v[224:225]
	v_pk_fma_f32 v[234:235], v[86:87], v[30:31], v[234:235]
	v_add_f32_dpp v172, v172, v172 quad_perm:[2,3,0,1] row_mask:0xf bank_mask:0xf bound_ctrl:1
	v_add_f32_dpp v174, v174, v174 quad_perm:[2,3,0,1] row_mask:0xf bank_mask:0xf bound_ctrl:1
	v_add_f32_dpp v160, v160, v160 quad_perm:[2,3,0,1] row_mask:0xf bank_mask:0xf bound_ctrl:1
	v_add_f32_dpp v161, v161, v161 quad_perm:[2,3,0,1] row_mask:0xf bank_mask:0xf bound_ctrl:1
	v_add_f32_dpp v172, v172, v172 row_half_mirror row_mask:0xf bank_mask:0xf bound_ctrl:1
	v_add_f32_dpp v174, v174, v174 row_half_mirror row_mask:0xf bank_mask:0xf bound_ctrl:1
	v_add_f32_dpp v160, v160, v160 row_half_mirror row_mask:0xf bank_mask:0xf bound_ctrl:1
	v_add_f32_dpp v161, v161, v161 row_half_mirror row_mask:0xf bank_mask:0xf bound_ctrl:1
	s_waitcnt lgkmcnt(13)
	v_pk_fma_f32 v[72:73], v[32:33], v[172:173], v[218:219] op_sel_hi:[1,0,1]
	v_pk_fma_f32 v[80:81], v[32:33], v[174:175], v[226:227] op_sel_hi:[1,0,1]
	v_pk_fma_f32 v[74:75], v[34:35], v[172:173], v[220:221] op_sel_hi:[1,0,1]
	v_pk_fma_f32 v[82:83], v[34:35], v[174:175], v[228:229] op_sel_hi:[1,0,1]
	s_waitcnt lgkmcnt(12)
	v_pk_fma_f32 v[76:77], v[36:37], v[172:173], v[222:223] op_sel_hi:[1,0,1]
	v_pk_fma_f32 v[84:85], v[36:37], v[174:175], v[230:231] op_sel_hi:[1,0,1]
	v_pk_fma_f32 v[78:79], v[38:39], v[172:173], v[224:225] op_sel_hi:[1,0,1]
	v_pk_fma_f32 v[86:87], v[38:39], v[174:175], v[234:235] op_sel_hi:[1,0,1]
	ds_write_b64 v1, v[160:161] offset:56064
	s_waitcnt lgkmcnt(9)
	v_pk_mul_f32 v[164:165], v[72:73], v[176:177]
	ds_read_b128 v[208:211], v2 offset:18944
	v_pk_mul_f32 v[166:167], v[80:81], v[176:177]
	ds_read_b128 v[212:215], v2 offset:18960
	v_pk_mul_f32 v[168:169], v[72:73], v[48:49]
	ds_read_b128 v[4:7], v2 offset:6912
	v_pk_mul_f32 v[170:171], v[80:81], v[48:49]
	ds_read_b128 v[8:11], v2 offset:6928
	v_pk_fma_f32 v[164:165], v[74:75], v[178:179], v[164:165]
	ds_read_b128 v[40:43], v2 offset:15104
	v_pk_fma_f32 v[166:167], v[82:83], v[178:179], v[166:167]
	ds_read_b128 v[44:47], v2 offset:15120
	v_pk_fma_f32 v[168:169], v[74:75], v[50:51], v[168:169]
	ds_read_b64 v[26:27], v3 offset:43776
	v_pk_fma_f32 v[170:171], v[82:83], v[50:51], v[170:171]
	ds_read_b128 v[12:15], v2 offset:2816
	s_waitcnt lgkmcnt(15)
	v_pk_fma_f32 v[164:165], v[76:77], v[180:181], v[164:165]
	ds_read_b128 v[28:31], v2 offset:2832
	v_pk_fma_f32 v[166:167], v[84:85], v[180:181], v[166:167]
	ds_read_b128 v[32:35], v2 offset:11008
	v_pk_fma_f32 v[168:169], v[76:77], v[52:53], v[168:169]
	ds_read_b128 v[36:39], v2 offset:11024
	v_pk_fma_f32 v[170:171], v[84:85], v[52:53], v[170:171]
	v_pk_fma_f32 v[164:165], v[78:79], v[182:183], v[164:165]
	v_pk_fma_f32 v[166:167], v[86:87], v[182:183], v[166:167]
	v_pk_fma_f32 v[168:169], v[78:79], v[54:55], v[168:169]
	v_pk_fma_f32 v[170:171], v[86:87], v[54:55], v[170:171]
	s_waitcnt lgkmcnt(15)
	v_pk_mul_f32 v[218:219], v[216:217], v[200:201] op_sel_hi:[0,1]
	v_pk_mul_f32 v[226:227], v[216:217], v[200:201] op_sel:[1,0]
	v_pk_mul_f32 v[220:221], v[216:217], v[202:203] op_sel_hi:[0,1]
	v_pk_mul_f32 v[228:229], v[216:217], v[202:203] op_sel:[1,0]
	v_pk_mul_f32 v[222:223], v[216:217], v[204:205] op_sel_hi:[0,1]
	v_pk_mul_f32 v[230:231], v[216:217], v[204:205] op_sel:[1,0]
	v_pk_mul_f32 v[224:225], v[216:217], v[206:207] op_sel_hi:[0,1]
	v_pk_mul_f32 v[234:235], v[216:217], v[206:207] op_sel:[1,0]
	v_add_f32_e32 v172, v164, v165
	v_add_f32_e32 v174, v166, v167
	v_add_f32_e32 v160, v168, v169
	v_add_f32_e32 v161, v170, v171
	s_waitcnt lgkmcnt(15)
	v_pk_fma_f32 v[218:219], v[72:73], v[184:185], v[218:219]
	v_pk_fma_f32 v[226:227], v[80:81], v[184:185], v[226:227]
	v_pk_fma_f32 v[220:221], v[74:75], v[186:187], v[220:221]
	v_pk_fma_f32 v[228:229], v[82:83], v[186:187], v[228:229]
	v_add_f32_dpp v172, v172, v172 quad_perm:[1,0,3,2] row_mask:0xf bank_mask:0xf bound_ctrl:1
	v_add_f32_dpp v174, v174, v174 quad_perm:[1,0,3,2] row_mask:0xf bank_mask:0xf bound_ctrl:1
	v_add_f32_dpp v160, v160, v160 quad_perm:[1,0,3,2] row_mask:0xf bank_mask:0xf bound_ctrl:1
	v_add_f32_dpp v161, v161, v161 quad_perm:[1,0,3,2] row_mask:0xf bank_mask:0xf bound_ctrl:1
	s_waitcnt lgkmcnt(14)
	v_pk_fma_f32 v[222:223], v[76:77], v[188:189], v[222:223]
	v_pk_fma_f32 v[230:231], v[84:85], v[188:189], v[230:231]
	v_pk_fma_f32 v[224:225], v[78:79], v[190:191], v[224:225]
	v_pk_fma_f32 v[234:235], v[86:87], v[190:191], v[234:235]
	v_add_f32_dpp v172, v172, v172 quad_perm:[2,3,0,1] row_mask:0xf bank_mask:0xf bound_ctrl:1
	v_add_f32_dpp v174, v174, v174 quad_perm:[2,3,0,1] row_mask:0xf bank_mask:0xf bound_ctrl:1
	v_add_f32_dpp v160, v160, v160 quad_perm:[2,3,0,1] row_mask:0xf bank_mask:0xf bound_ctrl:1
	v_add_f32_dpp v161, v161, v161 quad_perm:[2,3,0,1] row_mask:0xf bank_mask:0xf bound_ctrl:1
	v_add_f32_dpp v172, v172, v172 row_half_mirror row_mask:0xf bank_mask:0xf bound_ctrl:1
	v_add_f32_dpp v174, v174, v174 row_half_mirror row_mask:0xf bank_mask:0xf bound_ctrl:1
	v_add_f32_dpp v160, v160, v160 row_half_mirror row_mask:0xf bank_mask:0xf bound_ctrl:1
	v_add_f32_dpp v161, v161, v161 row_half_mirror row_mask:0xf bank_mask:0xf bound_ctrl:1
	s_waitcnt lgkmcnt(13)
	v_pk_fma_f32 v[72:73], v[192:193], v[172:173], v[218:219] op_sel_hi:[1,0,1]
	v_pk_fma_f32 v[80:81], v[192:193], v[174:175], v[226:227] op_sel_hi:[1,0,1]
	v_pk_fma_f32 v[74:75], v[194:195], v[172:173], v[220:221] op_sel_hi:[1,0,1]
	v_pk_fma_f32 v[82:83], v[194:195], v[174:175], v[228:229] op_sel_hi:[1,0,1]
	s_waitcnt lgkmcnt(12)
	v_pk_fma_f32 v[76:77], v[196:197], v[172:173], v[222:223] op_sel_hi:[1,0,1]
	v_pk_fma_f32 v[84:85], v[196:197], v[174:175], v[230:231] op_sel_hi:[1,0,1]
	v_pk_fma_f32 v[78:79], v[198:199], v[172:173], v[224:225] op_sel_hi:[1,0,1]
	v_pk_fma_f32 v[86:87], v[198:199], v[174:175], v[234:235] op_sel_hi:[1,0,1]
	ds_write_b64 v1, v[160:161] offset:56320
	s_waitcnt lgkmcnt(9)
	v_pk_mul_f32 v[164:165], v[72:73], v[4:5]
	ds_read_b128 v[48:51], v2 offset:19200
	v_pk_mul_f32 v[166:167], v[80:81], v[4:5]
	ds_read_b128 v[52:55], v2 offset:19216
	v_pk_mul_f32 v[168:169], v[72:73], v[208:209]
	ds_read_b128 v[176:179], v2 offset:7168
	v_pk_mul_f32 v[170:171], v[80:81], v[208:209]
	ds_read_b128 v[180:183], v2 offset:7184
	v_pk_fma_f32 v[164:165], v[74:75], v[6:7], v[164:165]
	ds_read_b128 v[200:203], v2 offset:15360
	v_pk_fma_f32 v[166:167], v[82:83], v[6:7], v[166:167]
	ds_read_b128 v[204:207], v2 offset:15376
	v_pk_fma_f32 v[168:169], v[74:75], v[210:211], v[168:169]
	ds_read_b64 v[216:217], v3 offset:44032
	v_pk_fma_f32 v[170:171], v[82:83], v[210:211], v[170:171]
	ds_read_b128 v[184:187], v2 offset:3072
	s_waitcnt lgkmcnt(15)
	v_pk_fma_f32 v[164:165], v[76:77], v[8:9], v[164:165]
	ds_read_b128 v[188:191], v2 offset:3088
	v_pk_fma_f32 v[166:167], v[84:85], v[8:9], v[166:167]
	ds_read_b128 v[192:195], v2 offset:11264
	v_pk_fma_f32 v[168:169], v[76:77], v[212:213], v[168:169]
	ds_read_b128 v[196:199], v2 offset:11280
	v_pk_fma_f32 v[170:171], v[84:85], v[212:213], v[170:171]
	v_pk_fma_f32 v[164:165], v[78:79], v[10:11], v[164:165]
	v_pk_fma_f32 v[166:167], v[86:87], v[10:11], v[166:167]
	v_pk_fma_f32 v[168:169], v[78:79], v[214:215], v[168:169]
	v_pk_fma_f32 v[170:171], v[86:87], v[214:215], v[170:171]
	s_waitcnt lgkmcnt(15)
	v_pk_mul_f32 v[218:219], v[26:27], v[40:41] op_sel_hi:[0,1]
	v_pk_mul_f32 v[226:227], v[26:27], v[40:41] op_sel:[1,0]
	v_pk_mul_f32 v[220:221], v[26:27], v[42:43] op_sel_hi:[0,1]
	v_pk_mul_f32 v[228:229], v[26:27], v[42:43] op_sel:[1,0]
	v_pk_mul_f32 v[222:223], v[26:27], v[44:45] op_sel_hi:[0,1]
	v_pk_mul_f32 v[230:231], v[26:27], v[44:45] op_sel:[1,0]
	v_pk_mul_f32 v[224:225], v[26:27], v[46:47] op_sel_hi:[0,1]
	v_pk_mul_f32 v[234:235], v[26:27], v[46:47] op_sel:[1,0]
	v_add_f32_e32 v172, v164, v165
	v_add_f32_e32 v174, v166, v167
	v_add_f32_e32 v160, v168, v169
	v_add_f32_e32 v161, v170, v171
	s_waitcnt lgkmcnt(15)
	v_pk_fma_f32 v[218:219], v[72:73], v[12:13], v[218:219]
	v_pk_fma_f32 v[226:227], v[80:81], v[12:13], v[226:227]
	v_pk_fma_f32 v[220:221], v[74:75], v[14:15], v[220:221]
	v_pk_fma_f32 v[228:229], v[82:83], v[14:15], v[228:229]
	v_add_f32_dpp v172, v172, v172 quad_perm:[1,0,3,2] row_mask:0xf bank_mask:0xf bound_ctrl:1
	v_add_f32_dpp v174, v174, v174 quad_perm:[1,0,3,2] row_mask:0xf bank_mask:0xf bound_ctrl:1
	v_add_f32_dpp v160, v160, v160 quad_perm:[1,0,3,2] row_mask:0xf bank_mask:0xf bound_ctrl:1
	v_add_f32_dpp v161, v161, v161 quad_perm:[1,0,3,2] row_mask:0xf bank_mask:0xf bound_ctrl:1
	s_waitcnt lgkmcnt(14)
	v_pk_fma_f32 v[222:223], v[76:77], v[28:29], v[222:223]
	v_pk_fma_f32 v[230:231], v[84:85], v[28:29], v[230:231]
	v_pk_fma_f32 v[224:225], v[78:79], v[30:31], v[224:225]
	v_pk_fma_f32 v[234:235], v[86:87], v[30:31], v[234:235]
	v_add_f32_dpp v172, v172, v172 quad_perm:[2,3,0,1] row_mask:0xf bank_mask:0xf bound_ctrl:1
	v_add_f32_dpp v174, v174, v174 quad_perm:[2,3,0,1] row_mask:0xf bank_mask:0xf bound_ctrl:1
	v_add_f32_dpp v160, v160, v160 quad_perm:[2,3,0,1] row_mask:0xf bank_mask:0xf bound_ctrl:1
	v_add_f32_dpp v161, v161, v161 quad_perm:[2,3,0,1] row_mask:0xf bank_mask:0xf bound_ctrl:1
	v_add_f32_dpp v172, v172, v172 row_half_mirror row_mask:0xf bank_mask:0xf bound_ctrl:1
	v_add_f32_dpp v174, v174, v174 row_half_mirror row_mask:0xf bank_mask:0xf bound_ctrl:1
	v_add_f32_dpp v160, v160, v160 row_half_mirror row_mask:0xf bank_mask:0xf bound_ctrl:1
	v_add_f32_dpp v161, v161, v161 row_half_mirror row_mask:0xf bank_mask:0xf bound_ctrl:1
	s_waitcnt lgkmcnt(13)
	v_pk_fma_f32 v[72:73], v[32:33], v[172:173], v[218:219] op_sel_hi:[1,0,1]
	v_pk_fma_f32 v[80:81], v[32:33], v[174:175], v[226:227] op_sel_hi:[1,0,1]
	v_pk_fma_f32 v[74:75], v[34:35], v[172:173], v[220:221] op_sel_hi:[1,0,1]
	v_pk_fma_f32 v[82:83], v[34:35], v[174:175], v[228:229] op_sel_hi:[1,0,1]
	s_waitcnt lgkmcnt(12)
	v_pk_fma_f32 v[76:77], v[36:37], v[172:173], v[222:223] op_sel_hi:[1,0,1]
	v_pk_fma_f32 v[84:85], v[36:37], v[174:175], v[230:231] op_sel_hi:[1,0,1]
	v_pk_fma_f32 v[78:79], v[38:39], v[172:173], v[224:225] op_sel_hi:[1,0,1]
	v_pk_fma_f32 v[86:87], v[38:39], v[174:175], v[234:235] op_sel_hi:[1,0,1]
	ds_write_b64 v1, v[160:161] offset:56576
	s_waitcnt lgkmcnt(9)
	v_pk_mul_f32 v[164:165], v[72:73], v[176:177]
	ds_read_b128 v[208:211], v2 offset:19456
	v_pk_mul_f32 v[166:167], v[80:81], v[176:177]
	ds_read_b128 v[212:215], v2 offset:19472
	v_pk_mul_f32 v[168:169], v[72:73], v[48:49]
	ds_read_b128 v[4:7], v2 offset:7424
	v_pk_mul_f32 v[170:171], v[80:81], v[48:49]
	ds_read_b128 v[8:11], v2 offset:7440
	v_pk_fma_f32 v[164:165], v[74:75], v[178:179], v[164:165]
	ds_read_b128 v[40:43], v2 offset:15616
	v_pk_fma_f32 v[166:167], v[82:83], v[178:179], v[166:167]
	ds_read_b128 v[44:47], v2 offset:15632
	v_pk_fma_f32 v[168:169], v[74:75], v[50:51], v[168:169]
	ds_read_b64 v[26:27], v3 offset:44288
	v_pk_fma_f32 v[170:171], v[82:83], v[50:51], v[170:171]
	ds_read_b128 v[12:15], v2 offset:3328
	s_waitcnt lgkmcnt(15)
	v_pk_fma_f32 v[164:165], v[76:77], v[180:181], v[164:165]
	ds_read_b128 v[28:31], v2 offset:3344
	v_pk_fma_f32 v[166:167], v[84:85], v[180:181], v[166:167]
	ds_read_b128 v[32:35], v2 offset:11520
	v_pk_fma_f32 v[168:169], v[76:77], v[52:53], v[168:169]
	ds_read_b128 v[36:39], v2 offset:11536
	v_pk_fma_f32 v[170:171], v[84:85], v[52:53], v[170:171]
	v_pk_fma_f32 v[164:165], v[78:79], v[182:183], v[164:165]
	v_pk_fma_f32 v[166:167], v[86:87], v[182:183], v[166:167]
	v_pk_fma_f32 v[168:169], v[78:79], v[54:55], v[168:169]
	v_pk_fma_f32 v[170:171], v[86:87], v[54:55], v[170:171]
	s_waitcnt lgkmcnt(15)
	v_pk_mul_f32 v[218:219], v[216:217], v[200:201] op_sel_hi:[0,1]
	v_pk_mul_f32 v[226:227], v[216:217], v[200:201] op_sel:[1,0]
	v_pk_mul_f32 v[220:221], v[216:217], v[202:203] op_sel_hi:[0,1]
	v_pk_mul_f32 v[228:229], v[216:217], v[202:203] op_sel:[1,0]
	v_pk_mul_f32 v[222:223], v[216:217], v[204:205] op_sel_hi:[0,1]
	v_pk_mul_f32 v[230:231], v[216:217], v[204:205] op_sel:[1,0]
	v_pk_mul_f32 v[224:225], v[216:217], v[206:207] op_sel_hi:[0,1]
	v_pk_mul_f32 v[234:235], v[216:217], v[206:207] op_sel:[1,0]
	v_add_f32_e32 v172, v164, v165
	v_add_f32_e32 v174, v166, v167
	v_add_f32_e32 v160, v168, v169
	v_add_f32_e32 v161, v170, v171
	s_waitcnt lgkmcnt(15)
	v_pk_fma_f32 v[218:219], v[72:73], v[184:185], v[218:219]
	v_pk_fma_f32 v[226:227], v[80:81], v[184:185], v[226:227]
	v_pk_fma_f32 v[220:221], v[74:75], v[186:187], v[220:221]
	v_pk_fma_f32 v[228:229], v[82:83], v[186:187], v[228:229]
	v_add_f32_dpp v172, v172, v172 quad_perm:[1,0,3,2] row_mask:0xf bank_mask:0xf bound_ctrl:1
	v_add_f32_dpp v174, v174, v174 quad_perm:[1,0,3,2] row_mask:0xf bank_mask:0xf bound_ctrl:1
	v_add_f32_dpp v160, v160, v160 quad_perm:[1,0,3,2] row_mask:0xf bank_mask:0xf bound_ctrl:1
	v_add_f32_dpp v161, v161, v161 quad_perm:[1,0,3,2] row_mask:0xf bank_mask:0xf bound_ctrl:1
	s_waitcnt lgkmcnt(14)
	v_pk_fma_f32 v[222:223], v[76:77], v[188:189], v[222:223]
	v_pk_fma_f32 v[230:231], v[84:85], v[188:189], v[230:231]
	v_pk_fma_f32 v[224:225], v[78:79], v[190:191], v[224:225]
	v_pk_fma_f32 v[234:235], v[86:87], v[190:191], v[234:235]
	v_add_f32_dpp v172, v172, v172 quad_perm:[2,3,0,1] row_mask:0xf bank_mask:0xf bound_ctrl:1
	v_add_f32_dpp v174, v174, v174 quad_perm:[2,3,0,1] row_mask:0xf bank_mask:0xf bound_ctrl:1
	v_add_f32_dpp v160, v160, v160 quad_perm:[2,3,0,1] row_mask:0xf bank_mask:0xf bound_ctrl:1
	v_add_f32_dpp v161, v161, v161 quad_perm:[2,3,0,1] row_mask:0xf bank_mask:0xf bound_ctrl:1
	v_add_f32_dpp v172, v172, v172 row_half_mirror row_mask:0xf bank_mask:0xf bound_ctrl:1
	v_add_f32_dpp v174, v174, v174 row_half_mirror row_mask:0xf bank_mask:0xf bound_ctrl:1
	v_add_f32_dpp v160, v160, v160 row_half_mirror row_mask:0xf bank_mask:0xf bound_ctrl:1
	v_add_f32_dpp v161, v161, v161 row_half_mirror row_mask:0xf bank_mask:0xf bound_ctrl:1
	s_waitcnt lgkmcnt(13)
	v_pk_fma_f32 v[72:73], v[192:193], v[172:173], v[218:219] op_sel_hi:[1,0,1]
	v_pk_fma_f32 v[80:81], v[192:193], v[174:175], v[226:227] op_sel_hi:[1,0,1]
	v_pk_fma_f32 v[74:75], v[194:195], v[172:173], v[220:221] op_sel_hi:[1,0,1]
	v_pk_fma_f32 v[82:83], v[194:195], v[174:175], v[228:229] op_sel_hi:[1,0,1]
	s_waitcnt lgkmcnt(12)
	v_pk_fma_f32 v[76:77], v[196:197], v[172:173], v[222:223] op_sel_hi:[1,0,1]
	v_pk_fma_f32 v[84:85], v[196:197], v[174:175], v[230:231] op_sel_hi:[1,0,1]
	v_pk_fma_f32 v[78:79], v[198:199], v[172:173], v[224:225] op_sel_hi:[1,0,1]
	v_pk_fma_f32 v[86:87], v[198:199], v[174:175], v[234:235] op_sel_hi:[1,0,1]
	ds_write_b64 v1, v[160:161] offset:56832
	s_waitcnt lgkmcnt(9)
	v_pk_mul_f32 v[164:165], v[72:73], v[4:5]
	ds_read_b128 v[48:51], v2 offset:19712
	v_pk_mul_f32 v[166:167], v[80:81], v[4:5]
	ds_read_b128 v[52:55], v2 offset:19728
	v_pk_mul_f32 v[168:169], v[72:73], v[208:209]
	ds_read_b128 v[176:179], v2 offset:7680
	v_pk_mul_f32 v[170:171], v[80:81], v[208:209]
	ds_read_b128 v[180:183], v2 offset:7696
	v_pk_fma_f32 v[164:165], v[74:75], v[6:7], v[164:165]
	ds_read_b128 v[200:203], v2 offset:15872
	v_pk_fma_f32 v[166:167], v[82:83], v[6:7], v[166:167]
	ds_read_b128 v[204:207], v2 offset:15888
	v_pk_fma_f32 v[168:169], v[74:75], v[210:211], v[168:169]
	ds_read_b64 v[216:217], v3 offset:44544
	v_pk_fma_f32 v[170:171], v[82:83], v[210:211], v[170:171]
	ds_read_b128 v[184:187], v2 offset:3584
	s_waitcnt lgkmcnt(15)
	v_pk_fma_f32 v[164:165], v[76:77], v[8:9], v[164:165]
	ds_read_b128 v[188:191], v2 offset:3600
	v_pk_fma_f32 v[166:167], v[84:85], v[8:9], v[166:167]
	ds_read_b128 v[192:195], v2 offset:11776
	v_pk_fma_f32 v[168:169], v[76:77], v[212:213], v[168:169]
	ds_read_b128 v[196:199], v2 offset:11792
	v_pk_fma_f32 v[170:171], v[84:85], v[212:213], v[170:171]
	v_pk_fma_f32 v[164:165], v[78:79], v[10:11], v[164:165]
	v_pk_fma_f32 v[166:167], v[86:87], v[10:11], v[166:167]
	v_pk_fma_f32 v[168:169], v[78:79], v[214:215], v[168:169]
	v_pk_fma_f32 v[170:171], v[86:87], v[214:215], v[170:171]
	s_waitcnt lgkmcnt(15)
	v_pk_mul_f32 v[218:219], v[26:27], v[40:41] op_sel_hi:[0,1]
	v_pk_mul_f32 v[226:227], v[26:27], v[40:41] op_sel:[1,0]
	v_pk_mul_f32 v[220:221], v[26:27], v[42:43] op_sel_hi:[0,1]
	v_pk_mul_f32 v[228:229], v[26:27], v[42:43] op_sel:[1,0]
	v_pk_mul_f32 v[222:223], v[26:27], v[44:45] op_sel_hi:[0,1]
	v_pk_mul_f32 v[230:231], v[26:27], v[44:45] op_sel:[1,0]
	v_pk_mul_f32 v[224:225], v[26:27], v[46:47] op_sel_hi:[0,1]
	v_pk_mul_f32 v[234:235], v[26:27], v[46:47] op_sel:[1,0]
	v_add_f32_e32 v172, v164, v165
	v_add_f32_e32 v174, v166, v167
	v_add_f32_e32 v160, v168, v169
	v_add_f32_e32 v161, v170, v171
	s_waitcnt lgkmcnt(15)
	v_pk_fma_f32 v[218:219], v[72:73], v[12:13], v[218:219]
	v_pk_fma_f32 v[226:227], v[80:81], v[12:13], v[226:227]
	v_pk_fma_f32 v[220:221], v[74:75], v[14:15], v[220:221]
	v_pk_fma_f32 v[228:229], v[82:83], v[14:15], v[228:229]
	v_add_f32_dpp v172, v172, v172 quad_perm:[1,0,3,2] row_mask:0xf bank_mask:0xf bound_ctrl:1
	v_add_f32_dpp v174, v174, v174 quad_perm:[1,0,3,2] row_mask:0xf bank_mask:0xf bound_ctrl:1
	v_add_f32_dpp v160, v160, v160 quad_perm:[1,0,3,2] row_mask:0xf bank_mask:0xf bound_ctrl:1
	v_add_f32_dpp v161, v161, v161 quad_perm:[1,0,3,2] row_mask:0xf bank_mask:0xf bound_ctrl:1
	s_waitcnt lgkmcnt(14)
	v_pk_fma_f32 v[222:223], v[76:77], v[28:29], v[222:223]
	v_pk_fma_f32 v[230:231], v[84:85], v[28:29], v[230:231]
	v_pk_fma_f32 v[224:225], v[78:79], v[30:31], v[224:225]
	v_pk_fma_f32 v[234:235], v[86:87], v[30:31], v[234:235]
	v_add_f32_dpp v172, v172, v172 quad_perm:[2,3,0,1] row_mask:0xf bank_mask:0xf bound_ctrl:1
	v_add_f32_dpp v174, v174, v174 quad_perm:[2,3,0,1] row_mask:0xf bank_mask:0xf bound_ctrl:1
	v_add_f32_dpp v160, v160, v160 quad_perm:[2,3,0,1] row_mask:0xf bank_mask:0xf bound_ctrl:1
	v_add_f32_dpp v161, v161, v161 quad_perm:[2,3,0,1] row_mask:0xf bank_mask:0xf bound_ctrl:1
	v_add_f32_dpp v172, v172, v172 row_half_mirror row_mask:0xf bank_mask:0xf bound_ctrl:1
	v_add_f32_dpp v174, v174, v174 row_half_mirror row_mask:0xf bank_mask:0xf bound_ctrl:1
	v_add_f32_dpp v160, v160, v160 row_half_mirror row_mask:0xf bank_mask:0xf bound_ctrl:1
	v_add_f32_dpp v161, v161, v161 row_half_mirror row_mask:0xf bank_mask:0xf bound_ctrl:1
	s_waitcnt lgkmcnt(13)
	v_pk_fma_f32 v[72:73], v[32:33], v[172:173], v[218:219] op_sel_hi:[1,0,1]
	v_pk_fma_f32 v[80:81], v[32:33], v[174:175], v[226:227] op_sel_hi:[1,0,1]
	v_pk_fma_f32 v[74:75], v[34:35], v[172:173], v[220:221] op_sel_hi:[1,0,1]
	v_pk_fma_f32 v[82:83], v[34:35], v[174:175], v[228:229] op_sel_hi:[1,0,1]
	s_waitcnt lgkmcnt(12)
	v_pk_fma_f32 v[76:77], v[36:37], v[172:173], v[222:223] op_sel_hi:[1,0,1]
	v_pk_fma_f32 v[84:85], v[36:37], v[174:175], v[230:231] op_sel_hi:[1,0,1]
	v_pk_fma_f32 v[78:79], v[38:39], v[172:173], v[224:225] op_sel_hi:[1,0,1]
	v_pk_fma_f32 v[86:87], v[38:39], v[174:175], v[234:235] op_sel_hi:[1,0,1]
	ds_write_b64 v1, v[160:161] offset:57088
	s_waitcnt lgkmcnt(9)
	v_pk_mul_f32 v[164:165], v[72:73], v[176:177]
	ds_read_b128 v[208:211], v2 offset:19968
	v_pk_mul_f32 v[166:167], v[80:81], v[176:177]
	ds_read_b128 v[212:215], v2 offset:19984
	v_pk_mul_f32 v[168:169], v[72:73], v[48:49]
	ds_read_b128 v[4:7], v2 offset:7936
	v_pk_mul_f32 v[170:171], v[80:81], v[48:49]
	ds_read_b128 v[8:11], v2 offset:7952
	v_pk_fma_f32 v[164:165], v[74:75], v[178:179], v[164:165]
	ds_read_b128 v[40:43], v2 offset:16128
	v_pk_fma_f32 v[166:167], v[82:83], v[178:179], v[166:167]
	ds_read_b128 v[44:47], v2 offset:16144
	v_pk_fma_f32 v[168:169], v[74:75], v[50:51], v[168:169]
	ds_read_b64 v[26:27], v3 offset:44800
	v_pk_fma_f32 v[170:171], v[82:83], v[50:51], v[170:171]
	ds_read_b128 v[12:15], v2 offset:3840
	s_waitcnt lgkmcnt(15)
	v_pk_fma_f32 v[164:165], v[76:77], v[180:181], v[164:165]
	ds_read_b128 v[28:31], v2 offset:3856
	v_pk_fma_f32 v[166:167], v[84:85], v[180:181], v[166:167]
	ds_read_b128 v[32:35], v2 offset:12032
	v_pk_fma_f32 v[168:169], v[76:77], v[52:53], v[168:169]
	ds_read_b128 v[36:39], v2 offset:12048
	v_pk_fma_f32 v[170:171], v[84:85], v[52:53], v[170:171]
	v_pk_fma_f32 v[164:165], v[78:79], v[182:183], v[164:165]
	v_pk_fma_f32 v[166:167], v[86:87], v[182:183], v[166:167]
	v_pk_fma_f32 v[168:169], v[78:79], v[54:55], v[168:169]
	v_pk_fma_f32 v[170:171], v[86:87], v[54:55], v[170:171]
	s_waitcnt lgkmcnt(15)
	v_pk_mul_f32 v[218:219], v[216:217], v[200:201] op_sel_hi:[0,1]
	v_pk_mul_f32 v[226:227], v[216:217], v[200:201] op_sel:[1,0]
	v_pk_mul_f32 v[220:221], v[216:217], v[202:203] op_sel_hi:[0,1]
	v_pk_mul_f32 v[228:229], v[216:217], v[202:203] op_sel:[1,0]
	v_pk_mul_f32 v[222:223], v[216:217], v[204:205] op_sel_hi:[0,1]
	v_pk_mul_f32 v[230:231], v[216:217], v[204:205] op_sel:[1,0]
	v_pk_mul_f32 v[224:225], v[216:217], v[206:207] op_sel_hi:[0,1]
	v_pk_mul_f32 v[234:235], v[216:217], v[206:207] op_sel:[1,0]
	v_add_f32_e32 v172, v164, v165
	v_add_f32_e32 v174, v166, v167
	v_add_f32_e32 v160, v168, v169
	v_add_f32_e32 v161, v170, v171
	s_waitcnt lgkmcnt(15)
	v_pk_fma_f32 v[218:219], v[72:73], v[184:185], v[218:219]
	v_pk_fma_f32 v[226:227], v[80:81], v[184:185], v[226:227]
	v_pk_fma_f32 v[220:221], v[74:75], v[186:187], v[220:221]
	v_pk_fma_f32 v[228:229], v[82:83], v[186:187], v[228:229]
	v_add_f32_dpp v172, v172, v172 quad_perm:[1,0,3,2] row_mask:0xf bank_mask:0xf bound_ctrl:1
	v_add_f32_dpp v174, v174, v174 quad_perm:[1,0,3,2] row_mask:0xf bank_mask:0xf bound_ctrl:1
	v_add_f32_dpp v160, v160, v160 quad_perm:[1,0,3,2] row_mask:0xf bank_mask:0xf bound_ctrl:1
	v_add_f32_dpp v161, v161, v161 quad_perm:[1,0,3,2] row_mask:0xf bank_mask:0xf bound_ctrl:1
	s_waitcnt lgkmcnt(14)
	v_pk_fma_f32 v[222:223], v[76:77], v[188:189], v[222:223]
	v_pk_fma_f32 v[230:231], v[84:85], v[188:189], v[230:231]
	v_pk_fma_f32 v[224:225], v[78:79], v[190:191], v[224:225]
	v_pk_fma_f32 v[234:235], v[86:87], v[190:191], v[234:235]
	v_add_f32_dpp v172, v172, v172 quad_perm:[2,3,0,1] row_mask:0xf bank_mask:0xf bound_ctrl:1
	v_add_f32_dpp v174, v174, v174 quad_perm:[2,3,0,1] row_mask:0xf bank_mask:0xf bound_ctrl:1
	v_add_f32_dpp v160, v160, v160 quad_perm:[2,3,0,1] row_mask:0xf bank_mask:0xf bound_ctrl:1
	v_add_f32_dpp v161, v161, v161 quad_perm:[2,3,0,1] row_mask:0xf bank_mask:0xf bound_ctrl:1
	v_add_f32_dpp v172, v172, v172 row_half_mirror row_mask:0xf bank_mask:0xf bound_ctrl:1
	v_add_f32_dpp v174, v174, v174 row_half_mirror row_mask:0xf bank_mask:0xf bound_ctrl:1
	v_add_f32_dpp v160, v160, v160 row_half_mirror row_mask:0xf bank_mask:0xf bound_ctrl:1
	v_add_f32_dpp v161, v161, v161 row_half_mirror row_mask:0xf bank_mask:0xf bound_ctrl:1
	s_waitcnt lgkmcnt(13)
	v_pk_fma_f32 v[72:73], v[192:193], v[172:173], v[218:219] op_sel_hi:[1,0,1]
	v_pk_fma_f32 v[80:81], v[192:193], v[174:175], v[226:227] op_sel_hi:[1,0,1]
	v_pk_fma_f32 v[74:75], v[194:195], v[172:173], v[220:221] op_sel_hi:[1,0,1]
	v_pk_fma_f32 v[82:83], v[194:195], v[174:175], v[228:229] op_sel_hi:[1,0,1]
	s_waitcnt lgkmcnt(12)
	v_pk_fma_f32 v[76:77], v[196:197], v[172:173], v[222:223] op_sel_hi:[1,0,1]
	v_pk_fma_f32 v[84:85], v[196:197], v[174:175], v[230:231] op_sel_hi:[1,0,1]
	v_pk_fma_f32 v[78:79], v[198:199], v[172:173], v[224:225] op_sel_hi:[1,0,1]
	v_pk_fma_f32 v[86:87], v[198:199], v[174:175], v[234:235] op_sel_hi:[1,0,1]
	ds_write_b64 v1, v[160:161] offset:57344
	s_waitcnt lgkmcnt(9)
	v_pk_mul_f32 v[164:165], v[72:73], v[4:5]
	ds_read_b128 v[48:51], v2 offset:20224
	v_pk_mul_f32 v[166:167], v[80:81], v[4:5]
	ds_read_b128 v[52:55], v2 offset:20240
	v_pk_mul_f32 v[168:169], v[72:73], v[208:209]
	v_pk_mul_f32 v[170:171], v[80:81], v[208:209]
	v_pk_fma_f32 v[164:165], v[74:75], v[6:7], v[164:165]
	v_pk_fma_f32 v[166:167], v[82:83], v[6:7], v[166:167]
	v_pk_fma_f32 v[168:169], v[74:75], v[210:211], v[168:169]
	v_pk_fma_f32 v[170:171], v[82:83], v[210:211], v[170:171]
	s_waitcnt lgkmcnt(10)
	v_pk_fma_f32 v[164:165], v[76:77], v[8:9], v[164:165]
	v_pk_fma_f32 v[166:167], v[84:85], v[8:9], v[166:167]
	v_pk_fma_f32 v[168:169], v[76:77], v[212:213], v[168:169]
	v_pk_fma_f32 v[170:171], v[84:85], v[212:213], v[170:171]
	v_pk_fma_f32 v[164:165], v[78:79], v[10:11], v[164:165]
	v_pk_fma_f32 v[166:167], v[86:87], v[10:11], v[166:167]
	v_pk_fma_f32 v[168:169], v[78:79], v[214:215], v[168:169]
	v_pk_fma_f32 v[170:171], v[86:87], v[214:215], v[170:171]
	s_waitcnt lgkmcnt(7)
	v_pk_mul_f32 v[218:219], v[26:27], v[40:41] op_sel_hi:[0,1]
	v_pk_mul_f32 v[226:227], v[26:27], v[40:41] op_sel:[1,0]
	v_pk_mul_f32 v[220:221], v[26:27], v[42:43] op_sel_hi:[0,1]
	v_pk_mul_f32 v[228:229], v[26:27], v[42:43] op_sel:[1,0]
	v_pk_mul_f32 v[222:223], v[26:27], v[44:45] op_sel_hi:[0,1]
	v_pk_mul_f32 v[230:231], v[26:27], v[44:45] op_sel:[1,0]
	v_pk_mul_f32 v[224:225], v[26:27], v[46:47] op_sel_hi:[0,1]
	v_pk_mul_f32 v[234:235], v[26:27], v[46:47] op_sel:[1,0]
	v_add_f32_e32 v172, v164, v165
	v_add_f32_e32 v174, v166, v167
	v_add_f32_e32 v160, v168, v169
	v_add_f32_e32 v161, v170, v171
	s_waitcnt lgkmcnt(6)
	v_pk_fma_f32 v[218:219], v[72:73], v[12:13], v[218:219]
	v_pk_fma_f32 v[226:227], v[80:81], v[12:13], v[226:227]
	v_pk_fma_f32 v[220:221], v[74:75], v[14:15], v[220:221]
	v_pk_fma_f32 v[228:229], v[82:83], v[14:15], v[228:229]
	v_add_f32_dpp v172, v172, v172 quad_perm:[1,0,3,2] row_mask:0xf bank_mask:0xf bound_ctrl:1
	v_add_f32_dpp v174, v174, v174 quad_perm:[1,0,3,2] row_mask:0xf bank_mask:0xf bound_ctrl:1
	v_add_f32_dpp v160, v160, v160 quad_perm:[1,0,3,2] row_mask:0xf bank_mask:0xf bound_ctrl:1
	v_add_f32_dpp v161, v161, v161 quad_perm:[1,0,3,2] row_mask:0xf bank_mask:0xf bound_ctrl:1
	s_waitcnt lgkmcnt(5)
	v_pk_fma_f32 v[222:223], v[76:77], v[28:29], v[222:223]
	v_pk_fma_f32 v[230:231], v[84:85], v[28:29], v[230:231]
	v_pk_fma_f32 v[224:225], v[78:79], v[30:31], v[224:225]
	v_pk_fma_f32 v[234:235], v[86:87], v[30:31], v[234:235]
	v_add_f32_dpp v172, v172, v172 quad_perm:[2,3,0,1] row_mask:0xf bank_mask:0xf bound_ctrl:1
	v_add_f32_dpp v174, v174, v174 quad_perm:[2,3,0,1] row_mask:0xf bank_mask:0xf bound_ctrl:1
	v_add_f32_dpp v160, v160, v160 quad_perm:[2,3,0,1] row_mask:0xf bank_mask:0xf bound_ctrl:1
	v_add_f32_dpp v161, v161, v161 quad_perm:[2,3,0,1] row_mask:0xf bank_mask:0xf bound_ctrl:1
	v_add_f32_dpp v172, v172, v172 row_half_mirror row_mask:0xf bank_mask:0xf bound_ctrl:1
	v_add_f32_dpp v174, v174, v174 row_half_mirror row_mask:0xf bank_mask:0xf bound_ctrl:1
	v_add_f32_dpp v160, v160, v160 row_half_mirror row_mask:0xf bank_mask:0xf bound_ctrl:1
	v_add_f32_dpp v161, v161, v161 row_half_mirror row_mask:0xf bank_mask:0xf bound_ctrl:1
	s_waitcnt lgkmcnt(4)
	v_pk_fma_f32 v[72:73], v[32:33], v[172:173], v[218:219] op_sel_hi:[1,0,1]
	v_pk_fma_f32 v[80:81], v[32:33], v[174:175], v[226:227] op_sel_hi:[1,0,1]
	v_pk_fma_f32 v[74:75], v[34:35], v[172:173], v[220:221] op_sel_hi:[1,0,1]
	v_pk_fma_f32 v[82:83], v[34:35], v[174:175], v[228:229] op_sel_hi:[1,0,1]
	s_waitcnt lgkmcnt(3)
	v_pk_fma_f32 v[76:77], v[36:37], v[172:173], v[222:223] op_sel_hi:[1,0,1]
	v_pk_fma_f32 v[84:85], v[36:37], v[174:175], v[230:231] op_sel_hi:[1,0,1]
	v_pk_fma_f32 v[78:79], v[38:39], v[172:173], v[224:225] op_sel_hi:[1,0,1]
	v_pk_fma_f32 v[86:87], v[38:39], v[174:175], v[234:235] op_sel_hi:[1,0,1]
	ds_write_b64 v1, v[160:161] offset:57600
	s_waitcnt lgkmcnt(2)
	v_pk_mul_f32 v[168:169], v[72:73], v[48:49]
	v_pk_mul_f32 v[170:171], v[80:81], v[48:49]
	v_pk_fma_f32 v[168:169], v[74:75], v[50:51], v[168:169]
	v_pk_fma_f32 v[170:171], v[82:83], v[50:51], v[170:171]
	s_waitcnt lgkmcnt(1)
	v_pk_fma_f32 v[168:169], v[76:77], v[52:53], v[168:169]
	v_pk_fma_f32 v[170:171], v[84:85], v[52:53], v[170:171]
	v_pk_fma_f32 v[168:169], v[78:79], v[54:55], v[168:169]
	v_pk_fma_f32 v[170:171], v[86:87], v[54:55], v[170:171]
	v_add_f32_e32 v160, v168, v169
	v_add_f32_e32 v161, v170, v171
	s_nop 0
	v_add_f32_dpp v160, v160, v160 quad_perm:[1,0,3,2] row_mask:0xf bank_mask:0xf bound_ctrl:1
	v_add_f32_dpp v161, v161, v161 quad_perm:[1,0,3,2] row_mask:0xf bank_mask:0xf bound_ctrl:1
	s_nop 0
	v_add_f32_dpp v160, v160, v160 quad_perm:[2,3,0,1] row_mask:0xf bank_mask:0xf bound_ctrl:1
	v_add_f32_dpp v161, v161, v161 quad_perm:[2,3,0,1] row_mask:0xf bank_mask:0xf bound_ctrl:1
	s_nop 0
	v_add_f32_dpp v160, v160, v160 row_half_mirror row_mask:0xf bank_mask:0xf bound_ctrl:1
	v_add_f32_dpp v161, v161, v161 row_half_mirror row_mask:0xf bank_mask:0xf bound_ctrl:1
	ds_write_b64 v1, v[160:161] offset:57856
	s_add_i32 s3, s2, 1
	s_mov_b64 s[36:37], 0
